# K-loop s_setprio flips removed (issue slots inside the MFMA-paced segments) on top of the P7 epilogue staging-load hoist, conditional conv-state waits and dead spill-reload removal
# speedup vs baseline: 1.0141x; 1.0141x over previous
; #define PG8_STAGE(bufoff, gbase, voff) do { _Pragma("unroll") for (int _i = 0; _i < 2; ++_i) \
;         __builtin_amdgcn_global_load_lds((const unsigned*)((const char*)(gbase) + (voff)[_i]), (LAS unsigned*)(lds + (bufoff) + ldsw + _i * 8192), 16, 0, 0); } while (0)
; #define PG8_LDA(dst, b, h) do { _Pragma("unroll") for (int m = 0; m < 4; ++m) _Pragma("unroll") for (int k = 0; k < 2; ++k) dst[m][k] = *(const LAS bf16x8*)(lds + PG8_SA(b, h) + aoff + m * 2048 + k * 1024); } while (0)
; #define PG8_LDB(dst, b, h) do { _Pragma("unroll") for (int n = 0; n < 2; ++n) _Pragma("unroll") for (int k = 0; k < 2; ++k) dst[n][k] = *(const LAS bf16x8*)(lds + PG8_SB(b, h) + boff + n * 2048 + k * 1024); } while (0)
; #define PG8_MMA(ai, bj, At, Bt) do { __builtin_amdgcn_s_setprio(1); _Pragma("unroll") for (int m = 0; m < 4; ++m) _Pragma("unroll") for (int n = 0; n < 2; ++n) _Pragma("unroll") for (int k = 0; k < 2; ++k) \
;         acc[ai][bj][m][n] = __builtin_amdgcn_mfma_f32_16x16x32_bf16(Bt[n][k], At[m][k], acc[ai][bj][m][n], 0, 0, 0); __builtin_amdgcn_s_setprio(0); } while (0)
; #define PG8_WAIT_V(n) asm volatile("s_waitcnt vmcnt(" #n ")" ::: "memory")
; #define PG8_WAIT_L(n) asm volatile("s_waitcnt lgkmcnt(" #n ")" ::: "memory")
; #define PG8_BAR __builtin_amdgcn_s_barrier()
; #define PG8_SCHED __builtin_amdgcn_sched_barrier(0)
;     DI void a_ready(const Unit& u) const { if (ctr && u.pm >= 128) wait_counter(ctr, target); }
; template <class Epi, class Sched>
; DI void gemm_phase(LAS unsigned char* lds, const int K, const Sched& S, const Epi& E, const int wid) {
;     ...
;         for (int t = 0; t < nt; t += 2) {
;             const bool last = (t == nt - 2);
;             const char* a1 = cA + (size_t)(t + 1) * kstep;
;             const char* a2 = last ? nA : cA + (size_t)(t + 2) * kstep; const char* b2 = last ? nB : cB + (size_t)(t + 2) * kstep;
;             const char* a3 = a2 + kstep; const char* b3 = b2 + kstep;
;             if (last && has_next) S.a_ready(nxt);
;             PG8_LDB(B0, 0, 0); PG8_LDB(B1, 0, 1); PG8_SCHED; PG8_LDA(At, 0, 0); PG8_STAGE(PG8_SA(1, 1), a1 + hstep, voffA);
;             PG8_WAIT_V(8); PG8_WAIT_L(0); PG8_BAR; PG8_MMA(0, 0, At, B0); PG8_MMA(0, 1, At, B1); PG8_BAR; PG8_SCHED;
;             PG8_LDA(At, 0, 1); PG8_STAGE(PG8_SB(0, 0), b2, voffB); PG8_STAGE(PG8_SB(0, 1), b2 + hstep, voffB); PG8_STAGE(PG8_SA(0, 0), a2, voffA);
.LBB0_96:
	ds_read_b128 v[128:131], v179
	ds_read_b128 v[132:135], v179 offset:1024
	ds_read_b128 v[136:139], v179 offset:2048
	ds_read_b128 v[140:143], v179 offset:3072
	ds_read_b128 v[144:147], v180
	ds_read_b128 v[164:167], v180 offset:1024
	ds_read_b128 v[168:171], v180 offset:2048
	ds_read_b128 v[172:175], v180 offset:3072
	s_add_u32 s18, s4, 0xfff80080
	s_addc_u32 s19, s5, -1
	s_cmp_eq_u32 s17, 28
	s_cselect_b32 s69, s9, s19
	s_cselect_b32 s68, s10, s18
	s_cselect_b32 s57, s11, s16
	s_cselect_b32 s56, s14, s15
	v_lshl_add_u64 v[204:205], s[4:5], 0, v[156:157]
	s_add_i32 m0, s22, 0xc000
	ds_read_b128 v[184:187], v181
	ds_read_b128 v[188:191], v181 offset:1024
	ds_read_b128 v[192:195], v181 offset:2048
	ds_read_b128 v[196:199], v181 offset:3072
	ds_read_b128 v[200:203], v181 offset:4096
	ds_read_b128 v[208:211], v181 offset:5120
	ds_read_b128 v[212:215], v181 offset:6144
	ds_read_b128 v[216:219], v181 offset:7168
	global_load_lds_dwordx4 v[204:205], off
	v_lshl_add_u64 v[204:205], s[4:5], 0, v[158:159]
	s_add_i32 m0, s22, 0xe000
	s_nop 0
	global_load_lds_dwordx4 v[204:205], off
	s_waitcnt vmcnt(8)
	s_waitcnt lgkmcnt(0)
	s_barrier
	s_waitcnt lgkmcnt(0)
	v_mfma_f32_16x16x32_bf16 v[124:127], v[128:131], v[184:187], v[124:127]
	v_mfma_f32_16x16x32_bf16 v[120:123], v[136:139], v[184:187], v[120:123]
	v_mfma_f32_16x16x32_bf16 v[116:119], v[128:131], v[192:195], v[116:119]
	v_mfma_f32_16x16x32_bf16 v[112:115], v[136:139], v[192:195], v[112:115]
	v_mfma_f32_16x16x32_bf16 v[100:103], v[128:131], v[200:203], v[100:103]
	v_mfma_f32_16x16x32_bf16 v[96:99], v[136:139], v[200:203], v[96:99]
	v_mfma_f32_16x16x32_bf16 v[84:87], v[128:131], v[212:215], v[84:87]
	v_mfma_f32_16x16x32_bf16 v[80:83], v[136:139], v[212:215], v[80:83]
	v_mfma_f32_16x16x32_bf16 v[124:127], v[132:135], v[188:191], v[124:127]
	v_mfma_f32_16x16x32_bf16 v[120:123], v[140:143], v[188:191], v[120:123]
	v_mfma_f32_16x16x32_bf16 v[116:119], v[132:135], v[196:199], v[116:119]
	v_mfma_f32_16x16x32_bf16 v[112:115], v[140:143], v[196:199], v[112:115]
	v_mfma_f32_16x16x32_bf16 v[100:103], v[132:135], v[208:211], v[100:103]
	v_mfma_f32_16x16x32_bf16 v[96:99], v[140:143], v[208:211], v[96:99]
	v_mfma_f32_16x16x32_bf16 v[84:87], v[132:135], v[216:219], v[84:87]
	v_mfma_f32_16x16x32_bf16 v[80:83], v[140:143], v[216:219], v[80:83]
	v_mfma_f32_16x16x32_bf16 v[108:111], v[144:147], v[184:187], v[108:111]
	v_mfma_f32_16x16x32_bf16 v[104:107], v[168:171], v[184:187], v[104:107]
	v_mfma_f32_16x16x32_bf16 v[92:95], v[144:147], v[192:195], v[92:95]
	v_mfma_f32_16x16x32_bf16 v[88:91], v[168:171], v[192:195], v[88:91]
	v_mfma_f32_16x16x32_bf16 v[76:79], v[144:147], v[200:203], v[76:79]
	v_mfma_f32_16x16x32_bf16 v[72:75], v[168:171], v[200:203], v[72:75]
	v_mfma_f32_16x16x32_bf16 v[68:71], v[144:147], v[212:215], v[68:71]
	v_mfma_f32_16x16x32_bf16 v[64:67], v[168:171], v[212:215], v[64:67]
	v_mfma_f32_16x16x32_bf16 v[108:111], v[164:167], v[188:191], v[108:111]
	v_mfma_f32_16x16x32_bf16 v[104:107], v[172:175], v[188:191], v[104:107]
	v_mfma_f32_16x16x32_bf16 v[92:95], v[164:167], v[196:199], v[92:95]
	v_mfma_f32_16x16x32_bf16 v[88:91], v[172:175], v[196:199], v[88:91]
	v_mfma_f32_16x16x32_bf16 v[76:79], v[164:167], v[208:211], v[76:79]
	v_mfma_f32_16x16x32_bf16 v[72:75], v[172:175], v[208:211], v[72:75]
	v_mfma_f32_16x16x32_bf16 v[68:71], v[164:167], v[216:219], v[68:71]
	v_mfma_f32_16x16x32_bf16 v[64:67], v[172:175], v[216:219], v[64:67]
	s_barrier
	s_add_i32 s18, s13, s95
	v_lshl_add_u64 v[204:205], s[56:57], 0, v[150:151]
	s_mov_b32 m0, s18
	ds_read_b128 v[184:187], v181 offset:16384
	ds_read_b128 v[188:191], v181 offset:17408
	ds_read_b128 v[192:195], v181 offset:18432
	ds_read_b128 v[196:199], v181 offset:19456
	ds_read_b128 v[200:203], v181 offset:20480
	ds_read_b128 v[208:211], v181 offset:21504
	ds_read_b128 v[212:215], v181 offset:22528
	ds_read_b128 v[216:219], v181 offset:23552
	global_load_lds_dwordx4 v[204:205], off
	s_add_i32 m0, s18, 0x2000
	s_add_u32 s18, s56, 0x80000
	v_lshl_add_u64 v[220:221], s[56:57], 0, v[154:155]
	s_addc_u32 s19, s57, 0
	s_add_i32 s20, s24, s95
	global_load_lds_dwordx4 v[220:221], off
	v_lshl_add_u64 v[222:223], s[18:19], 0, v[150:151]
	s_mov_b32 m0, s20
	v_lshl_add_u64 v[224:225], s[68:69], 0, v[152:153]
	global_load_lds_dwordx4 v[222:223], off
	v_lshl_add_u64 v[222:223], s[18:19], 0, v[154:155]
	s_add_i32 m0, s20, 0x2000
	s_nop 0
	global_load_lds_dwordx4 v[222:223], off
	v_lshl_add_u64 v[222:223], s[68:69], 0, v[148:149]
	s_mov_b32 m0, s22
	s_nop 0
	global_load_lds_dwordx4 v[222:223], off
	s_mov_b32 m0, s23
	s_nop 0
	global_load_lds_dwordx4 v[224:225], off
	s_waitcnt vmcnt(8)
	s_waitcnt lgkmcnt(0)
	s_barrier
; #define PG8_STAGE(bufoff, gbase, voff) do { _Pragma("unroll") for (int _i = 0; _i < 2; ++_i) \
;         __builtin_amdgcn_global_load_lds((const unsigned*)((const char*)(gbase) + (voff)[_i]), (LAS unsigned*)(lds + (bufoff) + ldsw + _i * 8192), 16, 0, 0); } while (0)
; #define PG8_LDA(dst, b, h) do { _Pragma("unroll") for (int m = 0; m < 4; ++m) _Pragma("unroll") for (int k = 0; k < 2; ++k) dst[m][k] = *(const LAS bf16x8*)(lds + PG8_SA(b, h) + aoff + m * 2048 + k * 1024); } while (0)
; #define PG8_LDB(dst, b, h) do { _Pragma("unroll") for (int n = 0; n < 2; ++n) _Pragma("unroll") for (int k = 0; k < 2; ++k) dst[n][k] = *(const LAS bf16x8*)(lds + PG8_SB(b, h) + boff + n * 2048 + k * 1024); } while (0)
; #define PG8_MMA(ai, bj, At, Bt) do { __builtin_amdgcn_s_setprio(1); _Pragma("unroll") for (int m = 0; m < 4; ++m) _Pragma("unroll") for (int n = 0; n < 2; ++n) _Pragma("unroll") for (int k = 0; k < 2; ++k) \
;         acc[ai][bj][m][n] = __builtin_amdgcn_mfma_f32_16x16x32_bf16(Bt[n][k], At[m][k], acc[ai][bj][m][n], 0, 0, 0); __builtin_amdgcn_s_setprio(0); } while (0)
; #define PG8_WAIT_V(n) asm volatile("s_waitcnt vmcnt(" #n ")" ::: "memory")
; #define PG8_WAIT_L(n) asm volatile("s_waitcnt lgkmcnt(" #n ")" ::: "memory")
; #define PG8_BAR __builtin_amdgcn_s_barrier()
; #define PG8_SCHED __builtin_amdgcn_sched_barrier(0)
; template <class Epi, class Sched>
; DI void gemm_phase(LAS unsigned char* lds, const int K, const Sched& S, const Epi& E, const int wid) {
;     ...
;             PG8_WAIT_V(8); PG8_WAIT_L(0); PG8_BAR; PG8_MMA(1, 0, At, B0); PG8_MMA(1, 1, At, B1); PG8_BAR; PG8_SCHED;
;             PG8_LDB(B0, 1, 0); PG8_LDB(B1, 1, 1); PG8_SCHED; PG8_LDA(At, 1, 0); PG8_STAGE(PG8_SA(0, 1), a2 + hstep, voffA);
;             PG8_WAIT_V(8); PG8_WAIT_L(0); PG8_BAR; PG8_MMA(0, 0, At, B0); PG8_MMA(0, 1, At, B1); PG8_BAR; PG8_SCHED;
	s_waitcnt lgkmcnt(0)
	v_mfma_f32_16x16x32_bf16 v[60:63], v[128:131], v[184:187], v[60:63]
	v_mfma_f32_16x16x32_bf16 v[56:59], v[136:139], v[184:187], v[56:59]
	v_mfma_f32_16x16x32_bf16 v[52:55], v[128:131], v[192:195], v[52:55]
	v_mfma_f32_16x16x32_bf16 v[48:51], v[136:139], v[192:195], v[48:51]
	v_mfma_f32_16x16x32_bf16 v[36:39], v[128:131], v[200:203], v[36:39]
	v_mfma_f32_16x16x32_bf16 v[32:35], v[136:139], v[200:203], v[32:35]
	v_mfma_f32_16x16x32_bf16 v[20:23], v[128:131], v[212:215], v[20:23]
	v_mfma_f32_16x16x32_bf16 v[16:19], v[136:139], v[212:215], v[16:19]
	v_mfma_f32_16x16x32_bf16 v[60:63], v[132:135], v[188:191], v[60:63]
	v_mfma_f32_16x16x32_bf16 v[56:59], v[140:143], v[188:191], v[56:59]
	v_mfma_f32_16x16x32_bf16 v[52:55], v[132:135], v[196:199], v[52:55]
	v_mfma_f32_16x16x32_bf16 v[48:51], v[140:143], v[196:199], v[48:51]
	v_mfma_f32_16x16x32_bf16 v[36:39], v[132:135], v[208:211], v[36:39]
	v_mfma_f32_16x16x32_bf16 v[32:35], v[140:143], v[208:211], v[32:35]
	v_mfma_f32_16x16x32_bf16 v[20:23], v[132:135], v[216:219], v[20:23]
	v_mfma_f32_16x16x32_bf16 v[16:19], v[140:143], v[216:219], v[16:19]
	v_mfma_f32_16x16x32_bf16 v[44:47], v[144:147], v[184:187], v[44:47]
	v_mfma_f32_16x16x32_bf16 v[40:43], v[168:171], v[184:187], v[40:43]
	v_mfma_f32_16x16x32_bf16 v[28:31], v[144:147], v[192:195], v[28:31]
	v_mfma_f32_16x16x32_bf16 v[24:27], v[168:171], v[192:195], v[24:27]
	v_mfma_f32_16x16x32_bf16 v[12:15], v[144:147], v[200:203], v[12:15]
	v_mfma_f32_16x16x32_bf16 v[8:11], v[168:171], v[200:203], v[8:11]
	v_mfma_f32_16x16x32_bf16 v[4:7], v[144:147], v[212:215], v[4:7]
	v_mfma_f32_16x16x32_bf16 v[0:3], v[168:171], v[212:215], v[0:3]
	v_mfma_f32_16x16x32_bf16 v[44:47], v[164:167], v[188:191], v[44:47]
	v_mfma_f32_16x16x32_bf16 v[40:43], v[172:175], v[188:191], v[40:43]
	v_mfma_f32_16x16x32_bf16 v[28:31], v[164:167], v[196:199], v[28:31]
	v_mfma_f32_16x16x32_bf16 v[24:27], v[172:175], v[196:199], v[24:27]
	v_mfma_f32_16x16x32_bf16 v[12:15], v[164:167], v[208:211], v[12:15]
	v_mfma_f32_16x16x32_bf16 v[8:11], v[172:175], v[208:211], v[8:11]
	v_mfma_f32_16x16x32_bf16 v[4:7], v[164:167], v[216:219], v[4:7]
	v_mfma_f32_16x16x32_bf16 v[0:3], v[172:175], v[216:219], v[0:3]
	s_barrier
	s_add_i32 s20, 0, 0x18000
	s_add_i32 s21, 0, 0x1c000
	v_add_u32_e32 v140, s20, v178
	v_add_u32_e32 v172, s21, v178
	ds_read_b128 v[128:131], v140
	ds_read_b128 v[132:135], v140 offset:1024
	ds_read_b128 v[136:139], v140 offset:2048
	ds_read_b128 v[140:143], v140 offset:3072
	ds_read_b128 v[144:147], v172
	ds_read_b128 v[164:167], v172 offset:1024
	ds_read_b128 v[168:171], v172 offset:2048
	ds_read_b128 v[172:175], v172 offset:3072
	s_add_u32 s18, s68, 0x80000
	s_addc_u32 s19, s69, 0
	s_mov_b32 m0, s26
	v_lshl_add_u64 v[226:227], s[18:19], 0, v[148:149]
	ds_read_b128 v[184:187], v181 offset:32768
	ds_read_b128 v[188:191], v181 offset:33792
	ds_read_b128 v[192:195], v181 offset:34816
	ds_read_b128 v[196:199], v181 offset:35840
	ds_read_b128 v[200:203], v181 offset:36864
	ds_read_b128 v[208:211], v181 offset:37888
	ds_read_b128 v[212:215], v181 offset:38912
	ds_read_b128 v[216:219], v181 offset:39936
	global_load_lds_dwordx4 v[226:227], off
	v_lshl_add_u64 v[226:227], s[18:19], 0, v[152:153]
	s_mov_b32 m0, s27
	s_nop 0
	global_load_lds_dwordx4 v[226:227], off
	s_waitcnt vmcnt(8)
	s_waitcnt lgkmcnt(0)
	s_barrier
	s_waitcnt lgkmcnt(0)
	v_mfma_f32_16x16x32_bf16 v[124:127], v[128:131], v[184:187], v[124:127]
	v_mfma_f32_16x16x32_bf16 v[120:123], v[136:139], v[184:187], v[120:123]
	v_mfma_f32_16x16x32_bf16 v[116:119], v[128:131], v[192:195], v[116:119]
	v_mfma_f32_16x16x32_bf16 v[112:115], v[136:139], v[192:195], v[112:115]
	v_mfma_f32_16x16x32_bf16 v[100:103], v[128:131], v[200:203], v[100:103]
	v_mfma_f32_16x16x32_bf16 v[96:99], v[136:139], v[200:203], v[96:99]
	v_mfma_f32_16x16x32_bf16 v[84:87], v[128:131], v[212:215], v[84:87]
	v_mfma_f32_16x16x32_bf16 v[80:83], v[136:139], v[212:215], v[80:83]
	v_mfma_f32_16x16x32_bf16 v[124:127], v[132:135], v[188:191], v[124:127]
	v_mfma_f32_16x16x32_bf16 v[120:123], v[140:143], v[188:191], v[120:123]
	v_mfma_f32_16x16x32_bf16 v[116:119], v[132:135], v[196:199], v[116:119]
	v_mfma_f32_16x16x32_bf16 v[112:115], v[140:143], v[196:199], v[112:115]
	v_mfma_f32_16x16x32_bf16 v[100:103], v[132:135], v[208:211], v[100:103]
	v_mfma_f32_16x16x32_bf16 v[96:99], v[140:143], v[208:211], v[96:99]
	v_mfma_f32_16x16x32_bf16 v[84:87], v[132:135], v[216:219], v[84:87]
	v_mfma_f32_16x16x32_bf16 v[80:83], v[140:143], v[216:219], v[80:83]
	v_mfma_f32_16x16x32_bf16 v[108:111], v[144:147], v[184:187], v[108:111]
	v_mfma_f32_16x16x32_bf16 v[104:107], v[168:171], v[184:187], v[104:107]
	v_mfma_f32_16x16x32_bf16 v[92:95], v[144:147], v[192:195], v[92:95]
	v_mfma_f32_16x16x32_bf16 v[88:91], v[168:171], v[192:195], v[88:91]
	v_mfma_f32_16x16x32_bf16 v[76:79], v[144:147], v[200:203], v[76:79]
	v_mfma_f32_16x16x32_bf16 v[72:75], v[168:171], v[200:203], v[72:75]
	v_mfma_f32_16x16x32_bf16 v[68:71], v[144:147], v[212:215], v[68:71]
	v_mfma_f32_16x16x32_bf16 v[64:67], v[168:171], v[212:215], v[64:67]
	v_mfma_f32_16x16x32_bf16 v[108:111], v[164:167], v[188:191], v[108:111]
	v_mfma_f32_16x16x32_bf16 v[104:107], v[172:175], v[188:191], v[104:107]
	v_mfma_f32_16x16x32_bf16 v[92:95], v[164:167], v[196:199], v[92:95]
	v_mfma_f32_16x16x32_bf16 v[88:91], v[172:175], v[196:199], v[88:91]
	v_mfma_f32_16x16x32_bf16 v[76:79], v[164:167], v[208:211], v[76:79]
	v_mfma_f32_16x16x32_bf16 v[72:75], v[172:175], v[208:211], v[72:75]
	v_mfma_f32_16x16x32_bf16 v[68:71], v[164:167], v[216:219], v[68:71]
	v_mfma_f32_16x16x32_bf16 v[64:67], v[172:175], v[216:219], v[64:67]
	s_barrier
; #define PG8_STAGE(bufoff, gbase, voff) do { _Pragma("unroll") for (int _i = 0; _i < 2; ++_i) \
;         __builtin_amdgcn_global_load_lds((const unsigned*)((const char*)(gbase) + (voff)[_i]), (LAS unsigned*)(lds + (bufoff) + ldsw + _i * 8192), 16, 0, 0); } while (0)
; #define PG8_LDA(dst, b, h) do { _Pragma("unroll") for (int m = 0; m < 4; ++m) _Pragma("unroll") for (int k = 0; k < 2; ++k) dst[m][k] = *(const LAS bf16x8*)(lds + PG8_SA(b, h) + aoff + m * 2048 + k * 1024); } while (0)
; #define PG8_MMA(ai, bj, At, Bt) do { __builtin_amdgcn_s_setprio(1); _Pragma("unroll") for (int m = 0; m < 4; ++m) _Pragma("unroll") for (int n = 0; n < 2; ++n) _Pragma("unroll") for (int k = 0; k < 2; ++k) \
;         acc[ai][bj][m][n] = __builtin_amdgcn_mfma_f32_16x16x32_bf16(Bt[n][k], At[m][k], acc[ai][bj][m][n], 0, 0, 0); __builtin_amdgcn_s_setprio(0); } while (0)
; #define PG8_WAIT_V(n) asm volatile("s_waitcnt vmcnt(" #n ")" ::: "memory")
; #define PG8_WAIT_L(n) asm volatile("s_waitcnt lgkmcnt(" #n ")" ::: "memory")
; #define PG8_BAR __builtin_amdgcn_s_barrier()
; #define PG8_SCHED __builtin_amdgcn_sched_barrier(0)
; template <class Epi, class Sched>
; DI void gemm_phase(LAS unsigned char* lds, const int K, const Sched& S, const Epi& E, const int wid) {
;     ...
;             PG8_LDA(At, 1, 1); PG8_STAGE(PG8_SB(1, 0), b3, voffB); PG8_STAGE(PG8_SB(1, 1), b3 + hstep, voffB); PG8_STAGE(PG8_SA(1, 0), a3, voffA);
;             PG8_WAIT_V(8); PG8_WAIT_L(0); PG8_BAR; PG8_MMA(1, 0, At, B0); PG8_MMA(1, 1, At, B1); PG8_BAR; PG8_SCHED;
;         }
	s_add_i32 s18, s20, s95
	v_lshl_add_u64 v[204:205], v[204:205], 0, s[42:43]
	s_mov_b32 m0, s18
	ds_read_b128 v[184:187], v181 offset:49152
	ds_read_b128 v[188:191], v181 offset:50176
	ds_read_b128 v[192:195], v181 offset:51200
	ds_read_b128 v[196:199], v181 offset:52224
	ds_read_b128 v[200:203], v181 offset:53248
	ds_read_b128 v[208:211], v181 offset:54272
	ds_read_b128 v[212:215], v181 offset:55296
	ds_read_b128 v[216:219], v181 offset:56320
	global_load_lds_dwordx4 v[204:205], off
	s_add_i32 m0, s18, 0x2000
	s_add_u32 s18, s56, 0x80080
	v_lshl_add_u64 v[204:205], v[220:221], 0, s[42:43]
	s_addc_u32 s19, s57, 0
	s_add_i32 s20, s21, s95
	global_load_lds_dwordx4 v[204:205], off
	v_lshl_add_u64 v[204:205], s[18:19], 0, v[150:151]
	s_mov_b32 m0, s20
	s_nop 0
	global_load_lds_dwordx4 v[204:205], off
	v_lshl_add_u64 v[204:205], s[18:19], 0, v[154:155]
	s_add_i32 m0, s20, 0x2000
	s_nop 0
	global_load_lds_dwordx4 v[204:205], off
	v_lshl_add_u64 v[204:205], v[222:223], 0, s[42:43]
	s_mov_b32 m0, s94
	s_nop 0
	global_load_lds_dwordx4 v[204:205], off
	v_lshl_add_u64 v[204:205], v[224:225], 0, s[42:43]
	s_mov_b32 m0, s96
	s_nop 0
	global_load_lds_dwordx4 v[204:205], off
	s_waitcnt vmcnt(8)
	s_waitcnt lgkmcnt(0)
	s_barrier
	s_waitcnt lgkmcnt(0)
	v_mfma_f32_16x16x32_bf16 v[60:63], v[128:131], v[184:187], v[60:63]
	v_mfma_f32_16x16x32_bf16 v[56:59], v[136:139], v[184:187], v[56:59]
	v_mfma_f32_16x16x32_bf16 v[52:55], v[128:131], v[192:195], v[52:55]
	v_mfma_f32_16x16x32_bf16 v[48:51], v[136:139], v[192:195], v[48:51]
	v_mfma_f32_16x16x32_bf16 v[36:39], v[128:131], v[200:203], v[36:39]
	v_mfma_f32_16x16x32_bf16 v[32:35], v[136:139], v[200:203], v[32:35]
	v_mfma_f32_16x16x32_bf16 v[20:23], v[128:131], v[212:215], v[20:23]
	v_mfma_f32_16x16x32_bf16 v[16:19], v[136:139], v[212:215], v[16:19]
	v_mfma_f32_16x16x32_bf16 v[60:63], v[132:135], v[188:191], v[60:63]
	v_mfma_f32_16x16x32_bf16 v[56:59], v[140:143], v[188:191], v[56:59]
	v_mfma_f32_16x16x32_bf16 v[52:55], v[132:135], v[196:199], v[52:55]
	v_mfma_f32_16x16x32_bf16 v[48:51], v[140:143], v[196:199], v[48:51]
	v_mfma_f32_16x16x32_bf16 v[36:39], v[132:135], v[208:211], v[36:39]
	v_mfma_f32_16x16x32_bf16 v[32:35], v[140:143], v[208:211], v[32:35]
	v_mfma_f32_16x16x32_bf16 v[20:23], v[132:135], v[216:219], v[20:23]
	v_mfma_f32_16x16x32_bf16 v[16:19], v[140:143], v[216:219], v[16:19]
	v_mfma_f32_16x16x32_bf16 v[44:47], v[144:147], v[184:187], v[44:47]
	v_mfma_f32_16x16x32_bf16 v[40:43], v[168:171], v[184:187], v[40:43]
	v_mfma_f32_16x16x32_bf16 v[28:31], v[144:147], v[192:195], v[28:31]
	v_mfma_f32_16x16x32_bf16 v[24:27], v[168:171], v[192:195], v[24:27]
	v_mfma_f32_16x16x32_bf16 v[12:15], v[144:147], v[200:203], v[12:15]
	v_mfma_f32_16x16x32_bf16 v[8:11], v[168:171], v[200:203], v[8:11]
	v_mfma_f32_16x16x32_bf16 v[4:7], v[144:147], v[212:215], v[4:7]
	v_mfma_f32_16x16x32_bf16 v[0:3], v[168:171], v[212:215], v[0:3]
	v_mfma_f32_16x16x32_bf16 v[44:47], v[164:167], v[188:191], v[44:47]
	v_mfma_f32_16x16x32_bf16 v[40:43], v[172:175], v[188:191], v[40:43]
	v_mfma_f32_16x16x32_bf16 v[28:31], v[164:167], v[196:199], v[28:31]
	v_mfma_f32_16x16x32_bf16 v[24:27], v[172:175], v[196:199], v[24:27]
	v_mfma_f32_16x16x32_bf16 v[12:15], v[164:167], v[208:211], v[12:15]
	v_mfma_f32_16x16x32_bf16 v[8:11], v[172:175], v[208:211], v[8:11]
	v_mfma_f32_16x16x32_bf16 v[4:7], v[164:167], v[216:219], v[4:7]
	v_mfma_f32_16x16x32_bf16 v[0:3], v[172:175], v[216:219], v[0:3]
	s_barrier
	s_add_i32 s17, s17, 2
	s_add_u32 s4, s4, 0x100
	s_addc_u32 s5, s5, 0
	s_add_u32 s15, s15, 0x100
	s_addc_u32 s16, s16, 0
	s_cmp_gt_u32 s17, 29
	s_cbranch_scc0 .LBB0_96
	v_readlane_b32 s4, v249, 25
	v_readlane_b32 s5, v249, 26
	s_and_b64 vcc, exec, s[4:5]
	s_cbranch_vccz .LBB0_99
	s_barrier

; #define PG8_STAGE(bufoff, gbase, voff) do { _Pragma("unroll") for (int _i = 0; _i < 2; ++_i) \
;         __builtin_amdgcn_global_load_lds((const unsigned*)((const char*)(gbase) + (voff)[_i]), (LAS unsigned*)(lds + (bufoff) + ldsw + _i * 8192), 16, 0, 0); } while (0)
; #define PG8_LDA(dst, b, h) do { _Pragma("unroll") for (int m = 0; m < 4; ++m) _Pragma("unroll") for (int k = 0; k < 2; ++k) dst[m][k] = *(const LAS bf16x8*)(lds + PG8_SA(b, h) + aoff + m * 2048 + k * 1024); } while (0)
; #define PG8_LDB(dst, b, h) do { _Pragma("unroll") for (int n = 0; n < 2; ++n) _Pragma("unroll") for (int k = 0; k < 2; ++k) dst[n][k] = *(const LAS bf16x8*)(lds + PG8_SB(b, h) + boff + n * 2048 + k * 1024); } while (0)
; #define PG8_MMA(ai, bj, At, Bt) do { __builtin_amdgcn_s_setprio(1); _Pragma("unroll") for (int m = 0; m < 4; ++m) _Pragma("unroll") for (int n = 0; n < 2; ++n) _Pragma("unroll") for (int k = 0; k < 2; ++k) \
;         acc[ai][bj][m][n] = __builtin_amdgcn_mfma_f32_16x16x32_bf16(Bt[n][k], At[m][k], acc[ai][bj][m][n], 0, 0, 0); __builtin_amdgcn_s_setprio(0); } while (0)
; #define PG8_WAIT_V(n) asm volatile("s_waitcnt vmcnt(" #n ")" ::: "memory")
; #define PG8_WAIT_L(n) asm volatile("s_waitcnt lgkmcnt(" #n ")" ::: "memory")
; #define PG8_BAR __builtin_amdgcn_s_barrier()
; #define PG8_SCHED __builtin_amdgcn_sched_barrier(0)
;     DI void a_ready(const Unit& u) const { if (ctr && u.pm >= 128) wait_counter(ctr, target); }
; template <class Epi, class Sched>
; DI void gemm_phase(LAS unsigned char* lds, const int K, const Sched& S, const Epi& E, const int wid) {
;     ...
;         for (int t = 0; t < nt; t += 2) {
;             const bool last = (t == nt - 2);
;             const char* a1 = cA + (size_t)(t + 1) * kstep;
;             const char* a2 = last ? nA : cA + (size_t)(t + 2) * kstep; const char* b2 = last ? nB : cB + (size_t)(t + 2) * kstep;
;             const char* a3 = a2 + kstep; const char* b3 = b2 + kstep;
;             if (last && has_next) S.a_ready(nxt);
;             PG8_LDB(B0, 0, 0); PG8_LDB(B1, 0, 1); PG8_SCHED; PG8_LDA(At, 0, 0); PG8_STAGE(PG8_SA(1, 1), a1 + hstep, voffA);
;             PG8_WAIT_V(8); PG8_WAIT_L(0); PG8_BAR; PG8_MMA(0, 0, At, B0); PG8_MMA(0, 1, At, B1); PG8_BAR; PG8_SCHED;
;             PG8_LDA(At, 0, 1); PG8_STAGE(PG8_SB(0, 0), b2, voffB); PG8_STAGE(PG8_SB(0, 1), b2 + hstep, voffB); PG8_STAGE(PG8_SA(0, 0), a2, voffA);
.LBB0_539:
	ds_read_b128 v[128:131], v208
	ds_read_b128 v[132:135], v208 offset:1024
	ds_read_b128 v[136:139], v208 offset:2048
	ds_read_b128 v[140:143], v208 offset:3072
	ds_read_b128 v[144:147], v209
	ds_read_b128 v[148:151], v209 offset:1024
	ds_read_b128 v[152:155], v209 offset:2048
	ds_read_b128 v[156:159], v209 offset:3072
	s_add_i32 s49, s4, 2
	s_add_u32 s0, s56, 0xfffc0080
	s_addc_u32 s1, s57, -1
	s_cmp_eq_u32 s30, s4
	s_cselect_b32 s4, s52, s45
	s_cselect_b32 s7, s51, s1
	s_cselect_b32 s6, s50, s0
	s_cselect_b32 s5, s53, s47
	s_add_i32 s89, s85, 0xc000
	v_lshl_add_u64 v[212:213], s[56:57], 0, v[184:185]
	s_mov_b32 m0, s89
	s_add_i32 s26, s85, 0xe000
	ds_read_b128 v[160:163], v210
	ds_read_b128 v[164:167], v210 offset:1024
	ds_read_b128 v[168:171], v210 offset:2048
	ds_read_b128 v[172:175], v210 offset:3072
	ds_read_b128 v[188:191], v210 offset:4096
	ds_read_b128 v[192:195], v210 offset:5120
	ds_read_b128 v[196:199], v210 offset:6144
	ds_read_b128 v[200:203], v210 offset:7168
	global_load_lds_dwordx4 v[212:213], off
	v_lshl_add_u64 v[212:213], s[56:57], 0, v[186:187]
	s_mov_b32 m0, s26
	s_nop 0
	global_load_lds_dwordx4 v[212:213], off
	s_waitcnt vmcnt(8)
	s_waitcnt lgkmcnt(0)
	s_barrier
	s_waitcnt lgkmcnt(0)
	v_mfma_f32_16x16x32_bf16 v[124:127], v[128:131], v[160:163], v[124:127]
	v_mfma_f32_16x16x32_bf16 v[120:123], v[136:139], v[160:163], v[120:123]
	v_mfma_f32_16x16x32_bf16 v[108:111], v[128:131], v[168:171], v[108:111]
	v_mfma_f32_16x16x32_bf16 v[104:107], v[136:139], v[168:171], v[104:107]
	v_mfma_f32_16x16x32_bf16 v[96:99], v[128:131], v[188:191], v[96:99]
	v_mfma_f32_16x16x32_bf16 v[88:91], v[136:139], v[188:191], v[88:91]
	v_mfma_f32_16x16x32_bf16 v[80:83], v[128:131], v[196:199], v[80:83]
	v_mfma_f32_16x16x32_bf16 v[72:75], v[136:139], v[196:199], v[72:75]
	v_mfma_f32_16x16x32_bf16 v[124:127], v[132:135], v[164:167], v[124:127]
	v_mfma_f32_16x16x32_bf16 v[120:123], v[140:143], v[164:167], v[120:123]
	v_mfma_f32_16x16x32_bf16 v[108:111], v[132:135], v[172:175], v[108:111]
	v_mfma_f32_16x16x32_bf16 v[104:107], v[140:143], v[172:175], v[104:107]
	v_mfma_f32_16x16x32_bf16 v[96:99], v[132:135], v[192:195], v[96:99]
	v_mfma_f32_16x16x32_bf16 v[88:91], v[140:143], v[192:195], v[88:91]
	v_mfma_f32_16x16x32_bf16 v[80:83], v[132:135], v[200:203], v[80:83]
	v_mfma_f32_16x16x32_bf16 v[72:75], v[140:143], v[200:203], v[72:75]
	v_mfma_f32_16x16x32_bf16 v[116:119], v[144:147], v[160:163], v[116:119]
	v_mfma_f32_16x16x32_bf16 v[112:115], v[152:155], v[160:163], v[112:115]
	v_mfma_f32_16x16x32_bf16 v[100:103], v[144:147], v[168:171], v[100:103]
	v_mfma_f32_16x16x32_bf16 v[92:95], v[152:155], v[168:171], v[92:95]
	v_mfma_f32_16x16x32_bf16 v[84:87], v[144:147], v[188:191], v[84:87]
	v_mfma_f32_16x16x32_bf16 v[76:79], v[152:155], v[188:191], v[76:79]
	v_mfma_f32_16x16x32_bf16 v[68:71], v[144:147], v[196:199], v[68:71]
	v_mfma_f32_16x16x32_bf16 v[64:67], v[152:155], v[196:199], v[64:67]
	v_mfma_f32_16x16x32_bf16 v[116:119], v[148:151], v[164:167], v[116:119]
	v_mfma_f32_16x16x32_bf16 v[112:115], v[156:159], v[164:167], v[112:115]
	v_mfma_f32_16x16x32_bf16 v[100:103], v[148:151], v[172:175], v[100:103]
	v_mfma_f32_16x16x32_bf16 v[92:95], v[156:159], v[172:175], v[92:95]
	v_mfma_f32_16x16x32_bf16 v[84:87], v[148:151], v[192:195], v[84:87]
	v_mfma_f32_16x16x32_bf16 v[76:79], v[156:159], v[192:195], v[76:79]
	v_mfma_f32_16x16x32_bf16 v[68:71], v[148:151], v[200:203], v[68:71]
	v_mfma_f32_16x16x32_bf16 v[64:67], v[156:159], v[200:203], v[64:67]
	s_barrier
	s_add_i32 s27, s70, s95
	s_add_i32 s22, s27, 0x2000
	v_lshl_add_u64 v[212:213], s[4:5], 0, v[178:179]
	s_mov_b32 m0, s27
	s_add_u32 s0, s4, 0x40000
	ds_read_b128 v[160:163], v210 offset:16384
	ds_read_b128 v[164:167], v210 offset:17408
	ds_read_b128 v[168:171], v210 offset:18432
	ds_read_b128 v[172:175], v210 offset:19456
	ds_read_b128 v[188:191], v210 offset:20480
	ds_read_b128 v[192:195], v210 offset:21504
	ds_read_b128 v[196:199], v210 offset:22528
	ds_read_b128 v[200:203], v210 offset:23552
	global_load_lds_dwordx4 v[212:213], off
	v_lshl_add_u64 v[214:215], s[4:5], 0, v[182:183]
	s_mov_b32 m0, s22
	s_addc_u32 s1, s5, 0
	s_add_i32 s23, s2, s95
	global_load_lds_dwordx4 v[214:215], off
	v_lshl_add_u64 v[216:217], s[0:1], 0, v[178:179]
	s_mov_b32 m0, s23
	s_add_i32 s87, s23, 0x2000
	global_load_lds_dwordx4 v[216:217], off
	v_lshl_add_u64 v[216:217], s[0:1], 0, v[182:183]
	s_mov_b32 m0, s87
	v_lshl_add_u64 v[218:219], s[6:7], 0, v[180:181]
	global_load_lds_dwordx4 v[216:217], off
	v_lshl_add_u64 v[216:217], s[6:7], 0, v[176:177]
	s_mov_b32 m0, s85
	s_nop 0
	global_load_lds_dwordx4 v[216:217], off
	s_mov_b32 m0, s33
	s_nop 0
	global_load_lds_dwordx4 v[218:219], off
	s_waitcnt vmcnt(8)
	s_waitcnt lgkmcnt(0)
	s_barrier
; #define PG8_STAGE(bufoff, gbase, voff) do { _Pragma("unroll") for (int _i = 0; _i < 2; ++_i) \
;         __builtin_amdgcn_global_load_lds((const unsigned*)((const char*)(gbase) + (voff)[_i]), (LAS unsigned*)(lds + (bufoff) + ldsw + _i * 8192), 16, 0, 0); } while (0)
; #define PG8_LDA(dst, b, h) do { _Pragma("unroll") for (int m = 0; m < 4; ++m) _Pragma("unroll") for (int k = 0; k < 2; ++k) dst[m][k] = *(const LAS bf16x8*)(lds + PG8_SA(b, h) + aoff + m * 2048 + k * 1024); } while (0)
; #define PG8_LDB(dst, b, h) do { _Pragma("unroll") for (int n = 0; n < 2; ++n) _Pragma("unroll") for (int k = 0; k < 2; ++k) dst[n][k] = *(const LAS bf16x8*)(lds + PG8_SB(b, h) + boff + n * 2048 + k * 1024); } while (0)
; #define PG8_MMA(ai, bj, At, Bt) do { __builtin_amdgcn_s_setprio(1); _Pragma("unroll") for (int m = 0; m < 4; ++m) _Pragma("unroll") for (int n = 0; n < 2; ++n) _Pragma("unroll") for (int k = 0; k < 2; ++k) \
;         acc[ai][bj][m][n] = __builtin_amdgcn_mfma_f32_16x16x32_bf16(Bt[n][k], At[m][k], acc[ai][bj][m][n], 0, 0, 0); __builtin_amdgcn_s_setprio(0); } while (0)
; #define PG8_WAIT_V(n) asm volatile("s_waitcnt vmcnt(" #n ")" ::: "memory")
; #define PG8_WAIT_L(n) asm volatile("s_waitcnt lgkmcnt(" #n ")" ::: "memory")
; #define PG8_BAR __builtin_amdgcn_s_barrier()
; #define PG8_SCHED __builtin_amdgcn_sched_barrier(0)
; template <class Epi, class Sched>
; DI void gemm_phase(LAS unsigned char* lds, const int K, const Sched& S, const Epi& E, const int wid) {
;     ...
;             PG8_WAIT_V(8); PG8_WAIT_L(0); PG8_BAR; PG8_MMA(1, 0, At, B0); PG8_MMA(1, 1, At, B1); PG8_BAR; PG8_SCHED;
;             PG8_LDB(B0, 1, 0); PG8_LDB(B1, 1, 1); PG8_SCHED; PG8_LDA(At, 1, 0); PG8_STAGE(PG8_SA(0, 1), a2 + hstep, voffA);
;             PG8_WAIT_V(8); PG8_WAIT_L(0); PG8_BAR; PG8_MMA(0, 0, At, B0); PG8_MMA(0, 1, At, B1); PG8_BAR; PG8_SCHED;
	s_waitcnt lgkmcnt(0)
	v_mfma_f32_16x16x32_bf16 v[60:63], v[128:131], v[160:163], v[60:63]
	v_mfma_f32_16x16x32_bf16 v[56:59], v[136:139], v[160:163], v[56:59]
	v_mfma_f32_16x16x32_bf16 v[48:51], v[128:131], v[168:171], v[48:51]
	v_mfma_f32_16x16x32_bf16 v[40:43], v[136:139], v[168:171], v[40:43]
	v_mfma_f32_16x16x32_bf16 v[32:35], v[128:131], v[188:191], v[32:35]
	v_mfma_f32_16x16x32_bf16 v[24:27], v[136:139], v[188:191], v[24:27]
	v_mfma_f32_16x16x32_bf16 v[16:19], v[128:131], v[196:199], v[16:19]
	v_mfma_f32_16x16x32_bf16 v[8:11], v[136:139], v[196:199], v[8:11]
	v_mfma_f32_16x16x32_bf16 v[60:63], v[132:135], v[164:167], v[60:63]
	v_mfma_f32_16x16x32_bf16 v[56:59], v[140:143], v[164:167], v[56:59]
	v_mfma_f32_16x16x32_bf16 v[48:51], v[132:135], v[172:175], v[48:51]
	v_mfma_f32_16x16x32_bf16 v[40:43], v[140:143], v[172:175], v[40:43]
	v_mfma_f32_16x16x32_bf16 v[32:35], v[132:135], v[192:195], v[32:35]
	v_mfma_f32_16x16x32_bf16 v[24:27], v[140:143], v[192:195], v[24:27]
	v_mfma_f32_16x16x32_bf16 v[16:19], v[132:135], v[200:203], v[16:19]
	v_mfma_f32_16x16x32_bf16 v[8:11], v[140:143], v[200:203], v[8:11]
	v_mfma_f32_16x16x32_bf16 v[52:55], v[144:147], v[160:163], v[52:55]
	v_mfma_f32_16x16x32_bf16 v[44:47], v[152:155], v[160:163], v[44:47]
	v_mfma_f32_16x16x32_bf16 v[36:39], v[144:147], v[168:171], v[36:39]
	v_mfma_f32_16x16x32_bf16 v[28:31], v[152:155], v[168:171], v[28:31]
	v_mfma_f32_16x16x32_bf16 v[20:23], v[144:147], v[188:191], v[20:23]
	v_mfma_f32_16x16x32_bf16 v[12:15], v[152:155], v[188:191], v[12:15]
	v_mfma_f32_16x16x32_bf16 v[4:7], v[144:147], v[196:199], v[4:7]
	v_mfma_f32_16x16x32_bf16 v[0:3], v[152:155], v[196:199], v[0:3]
	v_mfma_f32_16x16x32_bf16 v[52:55], v[148:151], v[164:167], v[52:55]
	v_mfma_f32_16x16x32_bf16 v[44:47], v[156:159], v[164:167], v[44:47]
	v_mfma_f32_16x16x32_bf16 v[36:39], v[148:151], v[172:175], v[36:39]
	v_mfma_f32_16x16x32_bf16 v[28:31], v[156:159], v[172:175], v[28:31]
	v_mfma_f32_16x16x32_bf16 v[20:23], v[148:151], v[192:195], v[20:23]
	v_mfma_f32_16x16x32_bf16 v[12:15], v[156:159], v[192:195], v[12:15]
	v_mfma_f32_16x16x32_bf16 v[4:7], v[148:151], v[200:203], v[4:7]
	v_mfma_f32_16x16x32_bf16 v[0:3], v[156:159], v[200:203], v[0:3]
	s_barrier
	s_add_i32 s96, 0, 0x18000
	s_add_i32 s90, 0, 0x1c000
	v_add_u32_e32 v140, s96, v207
	v_add_u32_e32 v156, s90, v207
	ds_read_b128 v[128:131], v140
	ds_read_b128 v[132:135], v140 offset:1024
	ds_read_b128 v[136:139], v140 offset:2048
	ds_read_b128 v[140:143], v140 offset:3072
	ds_read_b128 v[144:147], v156
	ds_read_b128 v[148:151], v156 offset:1024
	ds_read_b128 v[152:155], v156 offset:2048
	ds_read_b128 v[156:159], v156 offset:3072
	s_add_u32 s6, s6, 0x40000
	s_addc_u32 s7, s7, 0
	s_mov_b32 m0, s29
	v_lshl_add_u64 v[220:221], s[6:7], 0, v[176:177]
	ds_read_b128 v[160:163], v210 offset:32768
	ds_read_b128 v[164:167], v210 offset:33792
	ds_read_b128 v[168:171], v210 offset:34816
	ds_read_b128 v[172:175], v210 offset:35840
	ds_read_b128 v[188:191], v210 offset:36864
	ds_read_b128 v[192:195], v210 offset:37888
	ds_read_b128 v[196:199], v210 offset:38912
	ds_read_b128 v[200:203], v210 offset:39936
	global_load_lds_dwordx4 v[220:221], off
	v_lshl_add_u64 v[220:221], s[6:7], 0, v[180:181]
	s_mov_b32 m0, s97
	s_nop 0
	global_load_lds_dwordx4 v[220:221], off
	s_waitcnt vmcnt(8)
	s_waitcnt lgkmcnt(0)
	s_barrier
	s_waitcnt lgkmcnt(0)
	v_mfma_f32_16x16x32_bf16 v[124:127], v[128:131], v[160:163], v[124:127]
	v_mfma_f32_16x16x32_bf16 v[120:123], v[136:139], v[160:163], v[120:123]
	v_mfma_f32_16x16x32_bf16 v[108:111], v[128:131], v[168:171], v[108:111]
	v_mfma_f32_16x16x32_bf16 v[104:107], v[136:139], v[168:171], v[104:107]
	v_mfma_f32_16x16x32_bf16 v[96:99], v[128:131], v[188:191], v[96:99]
	v_mfma_f32_16x16x32_bf16 v[88:91], v[136:139], v[188:191], v[88:91]
	v_mfma_f32_16x16x32_bf16 v[80:83], v[128:131], v[196:199], v[80:83]
	v_mfma_f32_16x16x32_bf16 v[72:75], v[136:139], v[196:199], v[72:75]
	v_mfma_f32_16x16x32_bf16 v[124:127], v[132:135], v[164:167], v[124:127]
	v_mfma_f32_16x16x32_bf16 v[120:123], v[140:143], v[164:167], v[120:123]
	v_mfma_f32_16x16x32_bf16 v[108:111], v[132:135], v[172:175], v[108:111]
	v_mfma_f32_16x16x32_bf16 v[104:107], v[140:143], v[172:175], v[104:107]
	v_mfma_f32_16x16x32_bf16 v[96:99], v[132:135], v[192:195], v[96:99]
	v_mfma_f32_16x16x32_bf16 v[88:91], v[140:143], v[192:195], v[88:91]
	v_mfma_f32_16x16x32_bf16 v[80:83], v[132:135], v[200:203], v[80:83]
	v_mfma_f32_16x16x32_bf16 v[72:75], v[140:143], v[200:203], v[72:75]
	v_mfma_f32_16x16x32_bf16 v[116:119], v[144:147], v[160:163], v[116:119]
	v_mfma_f32_16x16x32_bf16 v[112:115], v[152:155], v[160:163], v[112:115]
	v_mfma_f32_16x16x32_bf16 v[100:103], v[144:147], v[168:171], v[100:103]
	v_mfma_f32_16x16x32_bf16 v[92:95], v[152:155], v[168:171], v[92:95]
	v_mfma_f32_16x16x32_bf16 v[84:87], v[144:147], v[188:191], v[84:87]
	v_mfma_f32_16x16x32_bf16 v[76:79], v[152:155], v[188:191], v[76:79]
	v_mfma_f32_16x16x32_bf16 v[68:71], v[144:147], v[196:199], v[68:71]
	v_mfma_f32_16x16x32_bf16 v[64:67], v[152:155], v[196:199], v[64:67]
	v_mfma_f32_16x16x32_bf16 v[116:119], v[148:151], v[164:167], v[116:119]
	v_mfma_f32_16x16x32_bf16 v[112:115], v[156:159], v[164:167], v[112:115]
	v_mfma_f32_16x16x32_bf16 v[100:103], v[148:151], v[172:175], v[100:103]
	v_mfma_f32_16x16x32_bf16 v[92:95], v[156:159], v[172:175], v[92:95]
	v_mfma_f32_16x16x32_bf16 v[84:87], v[148:151], v[192:195], v[84:87]
	v_mfma_f32_16x16x32_bf16 v[76:79], v[156:159], v[192:195], v[76:79]
	v_mfma_f32_16x16x32_bf16 v[68:71], v[148:151], v[200:203], v[68:71]
	v_mfma_f32_16x16x32_bf16 v[64:67], v[156:159], v[200:203], v[64:67]
	s_barrier
; #define PG8_STAGE(bufoff, gbase, voff) do { _Pragma("unroll") for (int _i = 0; _i < 2; ++_i) \
;         __builtin_amdgcn_global_load_lds((const unsigned*)((const char*)(gbase) + (voff)[_i]), (LAS unsigned*)(lds + (bufoff) + ldsw + _i * 8192), 16, 0, 0); } while (0)
; #define PG8_LDA(dst, b, h) do { _Pragma("unroll") for (int m = 0; m < 4; ++m) _Pragma("unroll") for (int k = 0; k < 2; ++k) dst[m][k] = *(const LAS bf16x8*)(lds + PG8_SA(b, h) + aoff + m * 2048 + k * 1024); } while (0)
; #define PG8_MMA(ai, bj, At, Bt) do { __builtin_amdgcn_s_setprio(1); _Pragma("unroll") for (int m = 0; m < 4; ++m) _Pragma("unroll") for (int n = 0; n < 2; ++n) _Pragma("unroll") for (int k = 0; k < 2; ++k) \
;         acc[ai][bj][m][n] = __builtin_amdgcn_mfma_f32_16x16x32_bf16(Bt[n][k], At[m][k], acc[ai][bj][m][n], 0, 0, 0); __builtin_amdgcn_s_setprio(0); } while (0)
; #define PG8_WAIT_V(n) asm volatile("s_waitcnt vmcnt(" #n ")" ::: "memory")
; #define PG8_WAIT_L(n) asm volatile("s_waitcnt lgkmcnt(" #n ")" ::: "memory")
; #define PG8_BAR __builtin_amdgcn_s_barrier()
; #define PG8_SCHED __builtin_amdgcn_sched_barrier(0)
; template <class Epi, class Sched>
; DI void gemm_phase(LAS unsigned char* lds, const int K, const Sched& S, const Epi& E, const int wid) {
;     ...
;             PG8_LDA(At, 1, 1); PG8_STAGE(PG8_SB(1, 0), b3, voffB); PG8_STAGE(PG8_SB(1, 1), b3 + hstep, voffB); PG8_STAGE(PG8_SA(1, 0), a3, voffA);
;             PG8_WAIT_V(8); PG8_WAIT_L(0); PG8_BAR; PG8_MMA(1, 0, At, B0); PG8_MMA(1, 1, At, B1); PG8_BAR; PG8_SCHED;
;         }
	s_add_i32 s94, s96, s95
	s_add_i32 s84, s94, 0x2000
	v_lshl_add_u64 v[212:213], v[212:213], 0, s[34:35]
	s_mov_b32 m0, s94
	s_add_u32 s4, s4, 0x40080
	ds_read_b128 v[160:163], v210 offset:49152
	ds_read_b128 v[164:167], v210 offset:50176
	ds_read_b128 v[168:171], v210 offset:51200
	ds_read_b128 v[172:175], v210 offset:52224
	ds_read_b128 v[188:191], v210 offset:53248
	ds_read_b128 v[192:195], v210 offset:54272
	ds_read_b128 v[196:199], v210 offset:55296
	ds_read_b128 v[200:203], v210 offset:56320
	global_load_lds_dwordx4 v[212:213], off
	v_lshl_add_u64 v[212:213], v[214:215], 0, s[34:35]
	s_mov_b32 m0, s84
	s_addc_u32 s5, s5, 0
	s_add_i32 s86, s90, s95
	global_load_lds_dwordx4 v[212:213], off
	v_lshl_add_u64 v[212:213], s[4:5], 0, v[178:179]
	s_mov_b32 m0, s86
	s_add_i32 s28, s86, 0x2000
	global_load_lds_dwordx4 v[212:213], off
	v_lshl_add_u64 v[212:213], s[4:5], 0, v[182:183]
	s_mov_b32 m0, s28
	s_nop 0
	global_load_lds_dwordx4 v[212:213], off
	v_lshl_add_u64 v[212:213], v[216:217], 0, s[34:35]
	s_mov_b32 m0, s91
	s_nop 0
	global_load_lds_dwordx4 v[212:213], off
	v_lshl_add_u64 v[212:213], v[218:219], 0, s[34:35]
	s_mov_b32 m0, s88
	s_nop 0
	global_load_lds_dwordx4 v[212:213], off
	s_waitcnt vmcnt(8)
	s_waitcnt lgkmcnt(0)
	s_barrier
	s_waitcnt lgkmcnt(0)
	v_mfma_f32_16x16x32_bf16 v[60:63], v[128:131], v[160:163], v[60:63]
	v_mfma_f32_16x16x32_bf16 v[56:59], v[136:139], v[160:163], v[56:59]
	v_mfma_f32_16x16x32_bf16 v[48:51], v[128:131], v[168:171], v[48:51]
	v_mfma_f32_16x16x32_bf16 v[40:43], v[136:139], v[168:171], v[40:43]
	v_mfma_f32_16x16x32_bf16 v[32:35], v[128:131], v[188:191], v[32:35]
	v_mfma_f32_16x16x32_bf16 v[24:27], v[136:139], v[188:191], v[24:27]
	v_mfma_f32_16x16x32_bf16 v[16:19], v[128:131], v[196:199], v[16:19]
	v_mfma_f32_16x16x32_bf16 v[8:11], v[136:139], v[196:199], v[8:11]
	v_mfma_f32_16x16x32_bf16 v[60:63], v[132:135], v[164:167], v[60:63]
	v_mfma_f32_16x16x32_bf16 v[56:59], v[140:143], v[164:167], v[56:59]
	v_mfma_f32_16x16x32_bf16 v[48:51], v[132:135], v[172:175], v[48:51]
	v_mfma_f32_16x16x32_bf16 v[40:43], v[140:143], v[172:175], v[40:43]
	v_mfma_f32_16x16x32_bf16 v[32:35], v[132:135], v[192:195], v[32:35]
	v_mfma_f32_16x16x32_bf16 v[24:27], v[140:143], v[192:195], v[24:27]
	v_mfma_f32_16x16x32_bf16 v[16:19], v[132:135], v[200:203], v[16:19]
	v_mfma_f32_16x16x32_bf16 v[8:11], v[140:143], v[200:203], v[8:11]
	v_mfma_f32_16x16x32_bf16 v[52:55], v[144:147], v[160:163], v[52:55]
	v_mfma_f32_16x16x32_bf16 v[44:47], v[152:155], v[160:163], v[44:47]
	v_mfma_f32_16x16x32_bf16 v[36:39], v[144:147], v[168:171], v[36:39]
	v_mfma_f32_16x16x32_bf16 v[28:31], v[152:155], v[168:171], v[28:31]
	v_mfma_f32_16x16x32_bf16 v[20:23], v[144:147], v[188:191], v[20:23]
	v_mfma_f32_16x16x32_bf16 v[12:15], v[152:155], v[188:191], v[12:15]
	v_mfma_f32_16x16x32_bf16 v[4:7], v[144:147], v[196:199], v[4:7]
	v_mfma_f32_16x16x32_bf16 v[0:3], v[152:155], v[196:199], v[0:3]
	v_mfma_f32_16x16x32_bf16 v[52:55], v[148:151], v[164:167], v[52:55]
	v_mfma_f32_16x16x32_bf16 v[44:47], v[156:159], v[164:167], v[44:47]
	v_mfma_f32_16x16x32_bf16 v[36:39], v[148:151], v[172:175], v[36:39]
	v_mfma_f32_16x16x32_bf16 v[28:31], v[156:159], v[172:175], v[28:31]
	v_mfma_f32_16x16x32_bf16 v[20:23], v[148:151], v[192:195], v[20:23]
	v_mfma_f32_16x16x32_bf16 v[12:15], v[156:159], v[192:195], v[12:15]
	v_mfma_f32_16x16x32_bf16 v[4:7], v[148:151], v[200:203], v[4:7]
	v_mfma_f32_16x16x32_bf16 v[0:3], v[156:159], v[200:203], v[0:3]
	s_barrier
	s_add_u32 s56, s56, 0x100
	s_addc_u32 s57, s57, 0
	s_add_u32 s45, s45, 0x100
	s_addc_u32 s47, s47, 0
	s_cmp_ge_u32 s49, s43
	s_mov_b32 s4, s49
	s_cbranch_scc0 .LBB0_539
	v_readlane_b32 s4, v249, 25
	v_readlane_b32 s5, v249, 26
	s_and_b64 vcc, exec, s[4:5]
	s_cbranch_vccz .LBB0_542
	s_barrier

; #define PG8_STAGE(bufoff, gbase, voff) do { _Pragma("unroll") for (int _i = 0; _i < 2; ++_i) \
;         __builtin_amdgcn_global_load_lds((const unsigned*)((const char*)(gbase) + (voff)[_i]), (LAS unsigned*)(lds + (bufoff) + ldsw + _i * 8192), 16, 0, 0); } while (0)
; #define PG8_LDA(dst, b, h) do { _Pragma("unroll") for (int m = 0; m < 4; ++m) _Pragma("unroll") for (int k = 0; k < 2; ++k) dst[m][k] = *(const LAS bf16x8*)(lds + PG8_SA(b, h) + aoff + m * 2048 + k * 1024); } while (0)
; #define PG8_LDB(dst, b, h) do { _Pragma("unroll") for (int n = 0; n < 2; ++n) _Pragma("unroll") for (int k = 0; k < 2; ++k) dst[n][k] = *(const LAS bf16x8*)(lds + PG8_SB(b, h) + boff + n * 2048 + k * 1024); } while (0)
; #define PG8_MMA(ai, bj, At, Bt) do { __builtin_amdgcn_s_setprio(1); _Pragma("unroll") for (int m = 0; m < 4; ++m) _Pragma("unroll") for (int n = 0; n < 2; ++n) _Pragma("unroll") for (int k = 0; k < 2; ++k) \
;         acc[ai][bj][m][n] = __builtin_amdgcn_mfma_f32_16x16x32_bf16(Bt[n][k], At[m][k], acc[ai][bj][m][n], 0, 0, 0); __builtin_amdgcn_s_setprio(0); } while (0)
; #define PG8_WAIT_V(n) asm volatile("s_waitcnt vmcnt(" #n ")" ::: "memory")
; #define PG8_WAIT_L(n) asm volatile("s_waitcnt lgkmcnt(" #n ")" ::: "memory")
; #define PG8_BAR __builtin_amdgcn_s_barrier()
; #define PG8_SCHED __builtin_amdgcn_sched_barrier(0)
;     DI void a_ready(const Unit& u) const { if (ctr && u.pm >= 128) wait_counter(ctr, target); }
; template <class Epi, class Sched>
; DI void gemm_phase(LAS unsigned char* lds, const int K, const Sched& S, const Epi& E, const int wid) {
;     ...
;         for (int t = 0; t < nt; t += 2) {
;             const bool last = (t == nt - 2);
;             const char* a1 = cA + (size_t)(t + 1) * kstep;
;             const char* a2 = last ? nA : cA + (size_t)(t + 2) * kstep; const char* b2 = last ? nB : cB + (size_t)(t + 2) * kstep;
;             const char* a3 = a2 + kstep; const char* b3 = b2 + kstep;
;             if (last && has_next) S.a_ready(nxt);
;             PG8_LDB(B0, 0, 0); PG8_LDB(B1, 0, 1); PG8_SCHED; PG8_LDA(At, 0, 0); PG8_STAGE(PG8_SA(1, 1), a1 + hstep, voffA);
;             PG8_WAIT_V(8); PG8_WAIT_L(0); PG8_BAR; PG8_MMA(0, 0, At, B0); PG8_MMA(0, 1, At, B1); PG8_BAR; PG8_SCHED;
;             PG8_LDA(At, 0, 1); PG8_STAGE(PG8_SB(0, 0), b2, voffB); PG8_STAGE(PG8_SB(0, 1), b2 + hstep, voffB); PG8_STAGE(PG8_SA(0, 0), a2, voffA);
.LBB0_706:
	s_or_b32 s44, s6, 1
	s_lshl_b64 s[20:21], s[44:45], 7
	s_add_u32 s15, s62, s20
	s_addc_u32 s24, s63, s21
	s_add_i32 s44, s6, 2
	v_add_u32_e32 v140, s70, v208
	v_add_u32_e32 v156, s2, v208
	s_lshl_b64 s[20:21], s[44:45], 7
	s_waitcnt lgkmcnt(0)
	ds_read_b128 v[128:131], v140
	ds_read_b128 v[132:135], v140 offset:1024
	ds_read_b128 v[136:139], v140 offset:2048
	ds_read_b128 v[140:143], v140 offset:3072
	ds_read_b128 v[144:147], v156
	ds_read_b128 v[148:151], v156 offset:1024
	ds_read_b128 v[152:155], v156 offset:2048
	ds_read_b128 v[156:159], v156 offset:3072
	s_add_u32 s25, s62, s20
	s_addc_u32 s39, s63, s21
	s_and_b64 s[6:7], s[4:5], exec
	s_cselect_b32 s7, s53, s39
	s_cselect_b32 s6, s52, s25
	s_add_u32 s20, s60, s20
	s_addc_u32 s21, s61, s21
	s_and_b64 s[4:5], s[4:5], exec
	s_cselect_b32 s5, s55, s21
	s_cselect_b32 s4, s54, s20
	s_add_u32 s20, s15, 0x80000
	s_addc_u32 s21, s24, 0
	s_mov_b32 m0, s89
	v_lshl_add_u64 v[200:201], s[20:21], 0, v[184:185]
	ds_read_b128 v[160:163], v210
	ds_read_b128 v[164:167], v210 offset:1024
	ds_read_b128 v[168:171], v210 offset:2048
	ds_read_b128 v[172:175], v210 offset:3072
	ds_read_b128 v[176:179], v210 offset:4096
	ds_read_b128 v[180:183], v210 offset:5120
	ds_read_b128 v[192:195], v210 offset:6144
	ds_read_b128 v[196:199], v210 offset:7168
	global_load_lds_dwordx4 v[200:201], off
	v_lshl_add_u64 v[200:201], s[20:21], 0, v[188:189]
	s_mov_b32 m0, s26
	s_nop 0
	global_load_lds_dwordx4 v[200:201], off
	s_waitcnt vmcnt(8)
	s_waitcnt lgkmcnt(0)
	s_barrier
	s_waitcnt lgkmcnt(0)
	v_mfma_f32_16x16x32_bf16 v[124:127], v[128:131], v[160:163], v[124:127]
	v_mfma_f32_16x16x32_bf16 v[120:123], v[136:139], v[160:163], v[120:123]
	v_mfma_f32_16x16x32_bf16 v[116:119], v[128:131], v[168:171], v[116:119]
	v_mfma_f32_16x16x32_bf16 v[112:115], v[136:139], v[168:171], v[112:115]
	v_mfma_f32_16x16x32_bf16 v[100:103], v[128:131], v[176:179], v[100:103]
	v_mfma_f32_16x16x32_bf16 v[96:99], v[136:139], v[176:179], v[96:99]
	v_mfma_f32_16x16x32_bf16 v[84:87], v[128:131], v[192:195], v[84:87]
	v_mfma_f32_16x16x32_bf16 v[80:83], v[136:139], v[192:195], v[80:83]
	v_mfma_f32_16x16x32_bf16 v[124:127], v[132:135], v[164:167], v[124:127]
	v_mfma_f32_16x16x32_bf16 v[120:123], v[140:143], v[164:167], v[120:123]
	v_mfma_f32_16x16x32_bf16 v[116:119], v[132:135], v[172:175], v[116:119]
	v_mfma_f32_16x16x32_bf16 v[112:115], v[140:143], v[172:175], v[112:115]
	v_mfma_f32_16x16x32_bf16 v[100:103], v[132:135], v[180:183], v[100:103]
	v_mfma_f32_16x16x32_bf16 v[96:99], v[140:143], v[180:183], v[96:99]
	v_mfma_f32_16x16x32_bf16 v[84:87], v[132:135], v[196:199], v[84:87]
	v_mfma_f32_16x16x32_bf16 v[80:83], v[140:143], v[196:199], v[80:83]
	v_mfma_f32_16x16x32_bf16 v[108:111], v[144:147], v[160:163], v[108:111]
	v_mfma_f32_16x16x32_bf16 v[104:107], v[152:155], v[160:163], v[104:107]
	v_mfma_f32_16x16x32_bf16 v[92:95], v[144:147], v[168:171], v[92:95]
	v_mfma_f32_16x16x32_bf16 v[88:91], v[152:155], v[168:171], v[88:91]
	v_mfma_f32_16x16x32_bf16 v[76:79], v[144:147], v[176:179], v[76:79]
	v_mfma_f32_16x16x32_bf16 v[72:75], v[152:155], v[176:179], v[72:75]
	v_mfma_f32_16x16x32_bf16 v[68:71], v[144:147], v[192:195], v[68:71]
	v_mfma_f32_16x16x32_bf16 v[64:67], v[152:155], v[192:195], v[64:67]
	v_mfma_f32_16x16x32_bf16 v[108:111], v[148:151], v[164:167], v[108:111]
	v_mfma_f32_16x16x32_bf16 v[104:107], v[156:159], v[164:167], v[104:107]
	v_mfma_f32_16x16x32_bf16 v[92:95], v[148:151], v[172:175], v[92:95]
	v_mfma_f32_16x16x32_bf16 v[88:91], v[156:159], v[172:175], v[88:91]
	v_mfma_f32_16x16x32_bf16 v[76:79], v[148:151], v[180:183], v[76:79]
	v_mfma_f32_16x16x32_bf16 v[72:75], v[156:159], v[180:183], v[72:75]
	v_mfma_f32_16x16x32_bf16 v[68:71], v[148:151], v[196:199], v[68:71]
	v_mfma_f32_16x16x32_bf16 v[64:67], v[156:159], v[196:199], v[64:67]
	s_barrier
	s_mov_b32 m0, s27
	v_lshl_add_u64 v[200:201], s[4:5], 0, v[186:187]
	s_add_u32 s20, s4, 0x80000
	ds_read_b128 v[160:163], v210 offset:16384
	ds_read_b128 v[164:167], v210 offset:17408
	ds_read_b128 v[168:171], v210 offset:18432
	ds_read_b128 v[172:175], v210 offset:19456
	ds_read_b128 v[176:179], v210 offset:20480
	ds_read_b128 v[180:183], v210 offset:21504
	ds_read_b128 v[192:195], v210 offset:22528
	ds_read_b128 v[196:199], v210 offset:23552
	global_load_lds_dwordx4 v[200:201], off
	v_lshl_add_u64 v[202:203], s[4:5], 0, v[190:191]
	s_mov_b32 m0, s22
	s_addc_u32 s21, s5, 0
	global_load_lds_dwordx4 v[202:203], off
	v_lshl_add_u64 v[204:205], s[20:21], 0, v[186:187]
	s_mov_b32 m0, s23
	v_lshl_add_u64 v[212:213], s[6:7], 0, v[188:189]
	global_load_lds_dwordx4 v[204:205], off
	v_lshl_add_u64 v[204:205], s[20:21], 0, v[190:191]
	s_mov_b32 m0, s87
	s_nop 0
	global_load_lds_dwordx4 v[204:205], off
	v_lshl_add_u64 v[204:205], s[6:7], 0, v[184:185]
	s_mov_b32 m0, s85
	s_nop 0
	global_load_lds_dwordx4 v[204:205], off
	s_mov_b32 m0, s33
	s_nop 0
	global_load_lds_dwordx4 v[212:213], off
	s_waitcnt vmcnt(8)
	s_waitcnt lgkmcnt(0)
	s_barrier
; #define PG8_STAGE(bufoff, gbase, voff) do { _Pragma("unroll") for (int _i = 0; _i < 2; ++_i) \
;         __builtin_amdgcn_global_load_lds((const unsigned*)((const char*)(gbase) + (voff)[_i]), (LAS unsigned*)(lds + (bufoff) + ldsw + _i * 8192), 16, 0, 0); } while (0)
; #define PG8_LDA(dst, b, h) do { _Pragma("unroll") for (int m = 0; m < 4; ++m) _Pragma("unroll") for (int k = 0; k < 2; ++k) dst[m][k] = *(const LAS bf16x8*)(lds + PG8_SA(b, h) + aoff + m * 2048 + k * 1024); } while (0)
; #define PG8_LDB(dst, b, h) do { _Pragma("unroll") for (int n = 0; n < 2; ++n) _Pragma("unroll") for (int k = 0; k < 2; ++k) dst[n][k] = *(const LAS bf16x8*)(lds + PG8_SB(b, h) + boff + n * 2048 + k * 1024); } while (0)
; #define PG8_MMA(ai, bj, At, Bt) do { __builtin_amdgcn_s_setprio(1); _Pragma("unroll") for (int m = 0; m < 4; ++m) _Pragma("unroll") for (int n = 0; n < 2; ++n) _Pragma("unroll") for (int k = 0; k < 2; ++k) \
;         acc[ai][bj][m][n] = __builtin_amdgcn_mfma_f32_16x16x32_bf16(Bt[n][k], At[m][k], acc[ai][bj][m][n], 0, 0, 0); __builtin_amdgcn_s_setprio(0); } while (0)
; #define PG8_WAIT_V(n) asm volatile("s_waitcnt vmcnt(" #n ")" ::: "memory")
; #define PG8_WAIT_L(n) asm volatile("s_waitcnt lgkmcnt(" #n ")" ::: "memory")
; #define PG8_BAR __builtin_amdgcn_s_barrier()
; #define PG8_SCHED __builtin_amdgcn_sched_barrier(0)
; template <class Epi, class Sched>
; DI void gemm_phase(LAS unsigned char* lds, const int K, const Sched& S, const Epi& E, const int wid) {
;     ...
;             PG8_WAIT_V(8); PG8_WAIT_L(0); PG8_BAR; PG8_MMA(1, 0, At, B0); PG8_MMA(1, 1, At, B1); PG8_BAR; PG8_SCHED;
;             PG8_LDB(B0, 1, 0); PG8_LDB(B1, 1, 1); PG8_SCHED; PG8_LDA(At, 1, 0); PG8_STAGE(PG8_SA(0, 1), a2 + hstep, voffA);
;             PG8_WAIT_V(8); PG8_WAIT_L(0); PG8_BAR; PG8_MMA(0, 0, At, B0); PG8_MMA(0, 1, At, B1); PG8_BAR; PG8_SCHED;
	s_waitcnt lgkmcnt(0)
	v_mfma_f32_16x16x32_bf16 v[60:63], v[128:131], v[160:163], v[60:63]
	v_mfma_f32_16x16x32_bf16 v[56:59], v[136:139], v[160:163], v[56:59]
	v_mfma_f32_16x16x32_bf16 v[52:55], v[128:131], v[168:171], v[52:55]
	v_mfma_f32_16x16x32_bf16 v[48:51], v[136:139], v[168:171], v[48:51]
	v_mfma_f32_16x16x32_bf16 v[36:39], v[128:131], v[176:179], v[36:39]
	v_mfma_f32_16x16x32_bf16 v[32:35], v[136:139], v[176:179], v[32:35]
	v_mfma_f32_16x16x32_bf16 v[20:23], v[128:131], v[192:195], v[20:23]
	v_mfma_f32_16x16x32_bf16 v[16:19], v[136:139], v[192:195], v[16:19]
	v_mfma_f32_16x16x32_bf16 v[60:63], v[132:135], v[164:167], v[60:63]
	v_mfma_f32_16x16x32_bf16 v[56:59], v[140:143], v[164:167], v[56:59]
	v_mfma_f32_16x16x32_bf16 v[52:55], v[132:135], v[172:175], v[52:55]
	v_mfma_f32_16x16x32_bf16 v[48:51], v[140:143], v[172:175], v[48:51]
	v_mfma_f32_16x16x32_bf16 v[36:39], v[132:135], v[180:183], v[36:39]
	v_mfma_f32_16x16x32_bf16 v[32:35], v[140:143], v[180:183], v[32:35]
	v_mfma_f32_16x16x32_bf16 v[20:23], v[132:135], v[196:199], v[20:23]
	v_mfma_f32_16x16x32_bf16 v[16:19], v[140:143], v[196:199], v[16:19]
	v_mfma_f32_16x16x32_bf16 v[44:47], v[144:147], v[160:163], v[44:47]
	v_mfma_f32_16x16x32_bf16 v[40:43], v[152:155], v[160:163], v[40:43]
	v_mfma_f32_16x16x32_bf16 v[28:31], v[144:147], v[168:171], v[28:31]
	v_mfma_f32_16x16x32_bf16 v[24:27], v[152:155], v[168:171], v[24:27]
	v_mfma_f32_16x16x32_bf16 v[12:15], v[144:147], v[176:179], v[12:15]
	v_mfma_f32_16x16x32_bf16 v[8:11], v[152:155], v[176:179], v[8:11]
	v_mfma_f32_16x16x32_bf16 v[4:7], v[144:147], v[192:195], v[4:7]
	v_mfma_f32_16x16x32_bf16 v[0:3], v[152:155], v[192:195], v[0:3]
	v_mfma_f32_16x16x32_bf16 v[44:47], v[148:151], v[164:167], v[44:47]
	v_mfma_f32_16x16x32_bf16 v[40:43], v[156:159], v[164:167], v[40:43]
	v_mfma_f32_16x16x32_bf16 v[28:31], v[148:151], v[172:175], v[28:31]
	v_mfma_f32_16x16x32_bf16 v[24:27], v[156:159], v[172:175], v[24:27]
	v_mfma_f32_16x16x32_bf16 v[12:15], v[148:151], v[180:183], v[12:15]
	v_mfma_f32_16x16x32_bf16 v[8:11], v[156:159], v[180:183], v[8:11]
	v_mfma_f32_16x16x32_bf16 v[4:7], v[148:151], v[196:199], v[4:7]
	v_mfma_f32_16x16x32_bf16 v[0:3], v[156:159], v[196:199], v[0:3]
	s_barrier
	v_add_u32_e32 v140, s96, v208
	v_add_u32_e32 v156, s90, v208
	ds_read_b128 v[128:131], v140
	ds_read_b128 v[132:135], v140 offset:1024
	ds_read_b128 v[136:139], v140 offset:2048
	ds_read_b128 v[140:143], v140 offset:3072
	ds_read_b128 v[144:147], v156
	ds_read_b128 v[148:151], v156 offset:1024
	ds_read_b128 v[152:155], v156 offset:2048
	ds_read_b128 v[156:159], v156 offset:3072
	s_add_u32 s6, s6, 0x80000
	s_addc_u32 s7, s7, 0
	s_mov_b32 m0, s29
	v_lshl_add_u64 v[214:215], s[6:7], 0, v[184:185]
	ds_read_b128 v[160:163], v210 offset:32768
	ds_read_b128 v[164:167], v210 offset:33792
	ds_read_b128 v[168:171], v210 offset:34816
	ds_read_b128 v[172:175], v210 offset:35840
	ds_read_b128 v[176:179], v210 offset:36864
	ds_read_b128 v[180:183], v210 offset:37888
	ds_read_b128 v[192:195], v210 offset:38912
	ds_read_b128 v[196:199], v210 offset:39936
	global_load_lds_dwordx4 v[214:215], off
	v_lshl_add_u64 v[214:215], s[6:7], 0, v[188:189]
	s_mov_b32 m0, s97
	s_nop 0
	global_load_lds_dwordx4 v[214:215], off
	s_waitcnt vmcnt(8)
	s_waitcnt lgkmcnt(0)
	s_barrier
	s_waitcnt lgkmcnt(0)
	v_mfma_f32_16x16x32_bf16 v[124:127], v[128:131], v[160:163], v[124:127]
	v_mfma_f32_16x16x32_bf16 v[120:123], v[136:139], v[160:163], v[120:123]
	v_mfma_f32_16x16x32_bf16 v[116:119], v[128:131], v[168:171], v[116:119]
	v_mfma_f32_16x16x32_bf16 v[112:115], v[136:139], v[168:171], v[112:115]
	v_mfma_f32_16x16x32_bf16 v[100:103], v[128:131], v[176:179], v[100:103]
	v_mfma_f32_16x16x32_bf16 v[96:99], v[136:139], v[176:179], v[96:99]
	v_mfma_f32_16x16x32_bf16 v[84:87], v[128:131], v[192:195], v[84:87]
	v_mfma_f32_16x16x32_bf16 v[80:83], v[136:139], v[192:195], v[80:83]
	v_mfma_f32_16x16x32_bf16 v[124:127], v[132:135], v[164:167], v[124:127]
	v_mfma_f32_16x16x32_bf16 v[120:123], v[140:143], v[164:167], v[120:123]
	v_mfma_f32_16x16x32_bf16 v[116:119], v[132:135], v[172:175], v[116:119]
	v_mfma_f32_16x16x32_bf16 v[112:115], v[140:143], v[172:175], v[112:115]
	v_mfma_f32_16x16x32_bf16 v[100:103], v[132:135], v[180:183], v[100:103]
	v_mfma_f32_16x16x32_bf16 v[96:99], v[140:143], v[180:183], v[96:99]
	v_mfma_f32_16x16x32_bf16 v[84:87], v[132:135], v[196:199], v[84:87]
	v_mfma_f32_16x16x32_bf16 v[80:83], v[140:143], v[196:199], v[80:83]
	v_mfma_f32_16x16x32_bf16 v[108:111], v[144:147], v[160:163], v[108:111]
	v_mfma_f32_16x16x32_bf16 v[104:107], v[152:155], v[160:163], v[104:107]
	v_mfma_f32_16x16x32_bf16 v[92:95], v[144:147], v[168:171], v[92:95]
	v_mfma_f32_16x16x32_bf16 v[88:91], v[152:155], v[168:171], v[88:91]
	v_mfma_f32_16x16x32_bf16 v[76:79], v[144:147], v[176:179], v[76:79]
	v_mfma_f32_16x16x32_bf16 v[72:75], v[152:155], v[176:179], v[72:75]
	v_mfma_f32_16x16x32_bf16 v[68:71], v[144:147], v[192:195], v[68:71]
	v_mfma_f32_16x16x32_bf16 v[64:67], v[152:155], v[192:195], v[64:67]
	v_mfma_f32_16x16x32_bf16 v[108:111], v[148:151], v[164:167], v[108:111]
	v_mfma_f32_16x16x32_bf16 v[104:107], v[156:159], v[164:167], v[104:107]
	v_mfma_f32_16x16x32_bf16 v[92:95], v[148:151], v[172:175], v[92:95]
	v_mfma_f32_16x16x32_bf16 v[88:91], v[156:159], v[172:175], v[88:91]
	v_mfma_f32_16x16x32_bf16 v[76:79], v[148:151], v[180:183], v[76:79]
	v_mfma_f32_16x16x32_bf16 v[72:75], v[156:159], v[180:183], v[72:75]
	v_mfma_f32_16x16x32_bf16 v[68:71], v[148:151], v[196:199], v[68:71]
	v_mfma_f32_16x16x32_bf16 v[64:67], v[156:159], v[196:199], v[64:67]
	s_barrier
; #define PG8_STAGE(bufoff, gbase, voff) do { _Pragma("unroll") for (int _i = 0; _i < 2; ++_i) \
;         __builtin_amdgcn_global_load_lds((const unsigned*)((const char*)(gbase) + (voff)[_i]), (LAS unsigned*)(lds + (bufoff) + ldsw + _i * 8192), 16, 0, 0); } while (0)
; #define PG8_LDA(dst, b, h) do { _Pragma("unroll") for (int m = 0; m < 4; ++m) _Pragma("unroll") for (int k = 0; k < 2; ++k) dst[m][k] = *(const LAS bf16x8*)(lds + PG8_SA(b, h) + aoff + m * 2048 + k * 1024); } while (0)
; #define PG8_MMA(ai, bj, At, Bt) do { __builtin_amdgcn_s_setprio(1); _Pragma("unroll") for (int m = 0; m < 4; ++m) _Pragma("unroll") for (int n = 0; n < 2; ++n) _Pragma("unroll") for (int k = 0; k < 2; ++k) \
;         acc[ai][bj][m][n] = __builtin_amdgcn_mfma_f32_16x16x32_bf16(Bt[n][k], At[m][k], acc[ai][bj][m][n], 0, 0, 0); __builtin_amdgcn_s_setprio(0); } while (0)
; #define PG8_WAIT_V(n) asm volatile("s_waitcnt vmcnt(" #n ")" ::: "memory")
; #define PG8_WAIT_L(n) asm volatile("s_waitcnt lgkmcnt(" #n ")" ::: "memory")
; #define PG8_BAR __builtin_amdgcn_s_barrier()
; #define PG8_SCHED __builtin_amdgcn_sched_barrier(0)
; template <class Epi, class Sched>
; DI void gemm_phase(LAS unsigned char* lds, const int K, const Sched& S, const Epi& E, const int wid) {
;     ...
;             PG8_LDA(At, 1, 1); PG8_STAGE(PG8_SB(1, 0), b3, voffB); PG8_STAGE(PG8_SB(1, 1), b3 + hstep, voffB); PG8_STAGE(PG8_SA(1, 0), a3, voffA);
;             PG8_WAIT_V(8); PG8_WAIT_L(0); PG8_BAR; PG8_MMA(1, 0, At, B0); PG8_MMA(1, 1, At, B1); PG8_BAR; PG8_SCHED;
;         }
	s_mov_b32 m0, s94
	v_lshl_add_u64 v[200:201], v[200:201], 0, s[46:47]
	s_add_u32 s4, s4, 0x80080
	ds_read_b128 v[160:163], v210 offset:49152
	ds_read_b128 v[164:167], v210 offset:50176
	ds_read_b128 v[168:171], v210 offset:51200
	ds_read_b128 v[172:175], v210 offset:52224
	ds_read_b128 v[176:179], v210 offset:53248
	ds_read_b128 v[180:183], v210 offset:54272
	ds_read_b128 v[192:195], v210 offset:55296
	ds_read_b128 v[196:199], v210 offset:56320
	global_load_lds_dwordx4 v[200:201], off
	v_lshl_add_u64 v[200:201], v[202:203], 0, s[46:47]
	s_mov_b32 m0, s84
	s_addc_u32 s5, s5, 0
	global_load_lds_dwordx4 v[200:201], off
	v_lshl_add_u64 v[200:201], s[4:5], 0, v[186:187]
	s_mov_b32 m0, s86
	s_nop 0
	global_load_lds_dwordx4 v[200:201], off
	v_lshl_add_u64 v[200:201], s[4:5], 0, v[190:191]
	s_mov_b32 m0, s28
	s_nop 0
	global_load_lds_dwordx4 v[200:201], off
	v_lshl_add_u64 v[200:201], v[204:205], 0, s[46:47]
	s_mov_b32 m0, s91
	s_nop 0
	global_load_lds_dwordx4 v[200:201], off
	v_lshl_add_u64 v[200:201], v[212:213], 0, s[46:47]
	s_mov_b32 m0, s88
	s_nop 0
	global_load_lds_dwordx4 v[200:201], off
	s_waitcnt vmcnt(8)
	s_waitcnt lgkmcnt(0)
	s_barrier
	s_waitcnt lgkmcnt(0)
	v_mfma_f32_16x16x32_bf16 v[60:63], v[128:131], v[160:163], v[60:63]
	v_mfma_f32_16x16x32_bf16 v[56:59], v[136:139], v[160:163], v[56:59]
	v_mfma_f32_16x16x32_bf16 v[52:55], v[128:131], v[168:171], v[52:55]
	v_mfma_f32_16x16x32_bf16 v[48:51], v[136:139], v[168:171], v[48:51]
	v_mfma_f32_16x16x32_bf16 v[36:39], v[128:131], v[176:179], v[36:39]
	v_mfma_f32_16x16x32_bf16 v[32:35], v[136:139], v[176:179], v[32:35]
	v_mfma_f32_16x16x32_bf16 v[20:23], v[128:131], v[192:195], v[20:23]
	v_mfma_f32_16x16x32_bf16 v[16:19], v[136:139], v[192:195], v[16:19]
	v_mfma_f32_16x16x32_bf16 v[60:63], v[132:135], v[164:167], v[60:63]
	v_mfma_f32_16x16x32_bf16 v[56:59], v[140:143], v[164:167], v[56:59]
	v_mfma_f32_16x16x32_bf16 v[52:55], v[132:135], v[172:175], v[52:55]
	v_mfma_f32_16x16x32_bf16 v[48:51], v[140:143], v[172:175], v[48:51]
	v_mfma_f32_16x16x32_bf16 v[36:39], v[132:135], v[180:183], v[36:39]
	v_mfma_f32_16x16x32_bf16 v[32:35], v[140:143], v[180:183], v[32:35]
	v_mfma_f32_16x16x32_bf16 v[20:23], v[132:135], v[196:199], v[20:23]
	v_mfma_f32_16x16x32_bf16 v[16:19], v[140:143], v[196:199], v[16:19]
	v_mfma_f32_16x16x32_bf16 v[44:47], v[144:147], v[160:163], v[44:47]
	v_mfma_f32_16x16x32_bf16 v[40:43], v[152:155], v[160:163], v[40:43]
	v_mfma_f32_16x16x32_bf16 v[28:31], v[144:147], v[168:171], v[28:31]
	v_mfma_f32_16x16x32_bf16 v[24:27], v[152:155], v[168:171], v[24:27]
	v_mfma_f32_16x16x32_bf16 v[12:15], v[144:147], v[176:179], v[12:15]
	v_mfma_f32_16x16x32_bf16 v[8:11], v[152:155], v[176:179], v[8:11]
	v_mfma_f32_16x16x32_bf16 v[4:7], v[144:147], v[192:195], v[4:7]
	v_mfma_f32_16x16x32_bf16 v[0:3], v[152:155], v[192:195], v[0:3]
	v_mfma_f32_16x16x32_bf16 v[44:47], v[148:151], v[164:167], v[44:47]
	v_mfma_f32_16x16x32_bf16 v[40:43], v[156:159], v[164:167], v[40:43]
	v_mfma_f32_16x16x32_bf16 v[28:31], v[148:151], v[172:175], v[28:31]
	v_mfma_f32_16x16x32_bf16 v[24:27], v[156:159], v[172:175], v[24:27]
	v_mfma_f32_16x16x32_bf16 v[12:15], v[148:151], v[180:183], v[12:15]
	v_mfma_f32_16x16x32_bf16 v[8:11], v[156:159], v[180:183], v[8:11]
	v_mfma_f32_16x16x32_bf16 v[4:7], v[148:151], v[196:199], v[4:7]
	v_mfma_f32_16x16x32_bf16 v[0:3], v[156:159], v[196:199], v[0:3]
	s_barrier
	s_cmp_ge_u32 s44, s11
	s_mov_b32 s6, s44
	s_cbranch_scc1 .LBB0_710

; #define PG8_STAGE(bufoff, gbase, voff) do { _Pragma("unroll") for (int _i = 0; _i < 2; ++_i) \
;         __builtin_amdgcn_global_load_lds((const unsigned*)((const char*)(gbase) + (voff)[_i]), (LAS unsigned*)(lds + (bufoff) + ldsw + _i * 8192), 16, 0, 0); } while (0)
; #define PG8_LDA(dst, b, h) do { _Pragma("unroll") for (int m = 0; m < 4; ++m) _Pragma("unroll") for (int k = 0; k < 2; ++k) dst[m][k] = *(const LAS bf16x8*)(lds + PG8_SA(b, h) + aoff + m * 2048 + k * 1024); } while (0)
; #define PG8_LDB(dst, b, h) do { _Pragma("unroll") for (int n = 0; n < 2; ++n) _Pragma("unroll") for (int k = 0; k < 2; ++k) dst[n][k] = *(const LAS bf16x8*)(lds + PG8_SB(b, h) + boff + n * 2048 + k * 1024); } while (0)
; #define PG8_MMA(ai, bj, At, Bt) do { __builtin_amdgcn_s_setprio(1); _Pragma("unroll") for (int m = 0; m < 4; ++m) _Pragma("unroll") for (int n = 0; n < 2; ++n) _Pragma("unroll") for (int k = 0; k < 2; ++k) \
;         acc[ai][bj][m][n] = __builtin_amdgcn_mfma_f32_16x16x32_bf16(Bt[n][k], At[m][k], acc[ai][bj][m][n], 0, 0, 0); __builtin_amdgcn_s_setprio(0); } while (0)
; #define PG8_WAIT_V(n) asm volatile("s_waitcnt vmcnt(" #n ")" ::: "memory")
; #define PG8_WAIT_L(n) asm volatile("s_waitcnt lgkmcnt(" #n ")" ::: "memory")
; #define PG8_BAR __builtin_amdgcn_s_barrier()
; #define PG8_SCHED __builtin_amdgcn_sched_barrier(0)
;     DI void a_ready(const Unit& u) const { if (ctr && u.pm >= 128) wait_counter(ctr, target); }
; template <class Epi, class Sched>
; DI void gemm_phase(LAS unsigned char* lds, const int K, const Sched& S, const Epi& E, const int wid) {
;     ...
;         for (int t = 0; t < nt; t += 2) {
;             const bool last = (t == nt - 2);
;             const char* a1 = cA + (size_t)(t + 1) * kstep;
;             const char* a2 = last ? nA : cA + (size_t)(t + 2) * kstep; const char* b2 = last ? nB : cB + (size_t)(t + 2) * kstep;
;             const char* a3 = a2 + kstep; const char* b3 = b2 + kstep;
;             if (last && has_next) S.a_ready(nxt);
;             PG8_LDB(B0, 0, 0); PG8_LDB(B1, 0, 1); PG8_SCHED; PG8_LDA(At, 0, 0); PG8_STAGE(PG8_SA(1, 1), a1 + hstep, voffA);
;             PG8_WAIT_V(8); PG8_WAIT_L(0); PG8_BAR; PG8_MMA(0, 0, At, B0); PG8_MMA(0, 1, At, B1); PG8_BAR; PG8_SCHED;
;             PG8_LDA(At, 0, 1); PG8_STAGE(PG8_SB(0, 0), b2, voffB); PG8_STAGE(PG8_SB(0, 1), b2 + hstep, voffB); PG8_STAGE(PG8_SA(0, 0), a2, voffA);
.LBB0_814:
	s_or_b32 s8, s54, 1
	s_lshl_b64 s[6:7], s[8:9], 7
	s_add_u32 s55, s50, s6
	s_addc_u32 s58, s51, s7
	s_add_i32 s8, s54, 2
	v_add_u32_e32 v108, s70, v198
	v_add_u32_e32 v124, s73, v198
	s_lshl_b64 s[56:57], s[8:9], 7
	ds_read_b128 v[96:99], v108
	ds_read_b128 v[100:103], v108 offset:1024
	ds_read_b128 v[104:107], v108 offset:2048
	ds_read_b128 v[108:111], v108 offset:3072
	ds_read_b128 v[112:115], v124
	ds_read_b128 v[116:119], v124 offset:1024
	ds_read_b128 v[120:123], v124 offset:2048
	ds_read_b128 v[124:127], v124 offset:3072
	s_add_u32 s59, s50, s56
	s_addc_u32 s60, s51, s57
	s_and_b64 s[6:7], s[4:5], exec
	s_cselect_b32 s7, s60, s35
	s_cselect_b32 s6, s59, s45
	s_add_u32 s56, s48, s56
	s_addc_u32 s57, s49, s57
	s_and_b64 s[4:5], s[4:5], exec
	s_cselect_b32 s5, s57, s31
	s_cselect_b32 s4, s56, s47
	s_add_u32 s56, s55, 0x80000
	s_addc_u32 s57, s58, 0
	s_mov_b32 m0, s89
	v_lshl_add_u64 v[194:195], s[56:57], 0, v[160:161]
	ds_read_b128 v[174:177], v199
	ds_read_b128 v[178:181], v199 offset:1024
	ds_read_b128 v[182:185], v199 offset:2048
	ds_read_b128 v[186:189], v199 offset:3072
	ds_read_b128 v[190:193], v199 offset:4096
	ds_read_b128 v[202:205], v199 offset:5120
	ds_read_b128 v[208:211], v199 offset:6144
	ds_read_b128 v[212:215], v199 offset:7168
	global_load_lds_dwordx4 v[194:195], off
	v_lshl_add_u64 v[194:195], s[56:57], 0, v[164:165]
	s_mov_b32 m0, s26
	s_nop 0
	global_load_lds_dwordx4 v[194:195], off
	s_waitcnt vmcnt(8)
	s_waitcnt lgkmcnt(0)
	s_barrier
	s_waitcnt lgkmcnt(0)
	v_mfma_f32_16x16x32_bf16 v[156:159], v[96:99], v[174:177], v[156:159]
	v_mfma_f32_16x16x32_bf16 v[60:63], v[104:107], v[174:177], v[60:63]
	v_mfma_f32_16x16x32_bf16 v[148:151], v[96:99], v[182:185], v[148:151]
	v_mfma_f32_16x16x32_bf16 v[52:55], v[104:107], v[182:185], v[52:55]
	v_mfma_f32_16x16x32_bf16 v[144:147], v[96:99], v[190:193], v[144:147]
	v_mfma_f32_16x16x32_bf16 v[48:51], v[104:107], v[190:193], v[48:51]
	v_mfma_f32_16x16x32_bf16 v[152:155], v[96:99], v[208:211], v[152:155]
	v_mfma_f32_16x16x32_bf16 v[56:59], v[104:107], v[208:211], v[56:59]
	v_mfma_f32_16x16x32_bf16 v[156:159], v[100:103], v[178:181], v[156:159]
	v_mfma_f32_16x16x32_bf16 v[60:63], v[108:111], v[178:181], v[60:63]
	v_mfma_f32_16x16x32_bf16 v[148:151], v[100:103], v[186:189], v[148:151]
	v_mfma_f32_16x16x32_bf16 v[52:55], v[108:111], v[186:189], v[52:55]
	v_mfma_f32_16x16x32_bf16 v[144:147], v[100:103], v[202:205], v[144:147]
	v_mfma_f32_16x16x32_bf16 v[48:51], v[108:111], v[202:205], v[48:51]
	v_mfma_f32_16x16x32_bf16 v[152:155], v[100:103], v[212:215], v[152:155]
	v_mfma_f32_16x16x32_bf16 v[56:59], v[108:111], v[212:215], v[56:59]
	v_mfma_f32_16x16x32_bf16 v[140:143], v[112:115], v[174:177], v[140:143]
	v_mfma_f32_16x16x32_bf16 v[44:47], v[120:123], v[174:177], v[44:47]
	v_mfma_f32_16x16x32_bf16 v[132:135], v[112:115], v[182:185], v[132:135]
	v_mfma_f32_16x16x32_bf16 v[36:39], v[120:123], v[182:185], v[36:39]
	v_mfma_f32_16x16x32_bf16 v[128:131], v[112:115], v[190:193], v[128:131]
	v_mfma_f32_16x16x32_bf16 v[32:35], v[120:123], v[190:193], v[32:35]
	v_mfma_f32_16x16x32_bf16 v[136:139], v[112:115], v[208:211], v[136:139]
	v_mfma_f32_16x16x32_bf16 v[40:43], v[120:123], v[208:211], v[40:43]
	v_mfma_f32_16x16x32_bf16 v[140:143], v[116:119], v[178:181], v[140:143]
	v_mfma_f32_16x16x32_bf16 v[44:47], v[124:127], v[178:181], v[44:47]
	v_mfma_f32_16x16x32_bf16 v[132:135], v[116:119], v[186:189], v[132:135]
	v_mfma_f32_16x16x32_bf16 v[36:39], v[124:127], v[186:189], v[36:39]
	v_mfma_f32_16x16x32_bf16 v[128:131], v[116:119], v[202:205], v[128:131]
	v_mfma_f32_16x16x32_bf16 v[32:35], v[124:127], v[202:205], v[32:35]
	v_mfma_f32_16x16x32_bf16 v[136:139], v[116:119], v[212:215], v[136:139]
	v_mfma_f32_16x16x32_bf16 v[40:43], v[124:127], v[212:215], v[40:43]
	s_barrier
	s_mov_b32 m0, s27
	v_lshl_add_u64 v[194:195], s[4:5], 0, v[162:163]
	s_add_u32 s56, s4, 0x80000
	ds_read_b128 v[174:177], v199 offset:16384
	ds_read_b128 v[178:181], v199 offset:17408
	ds_read_b128 v[182:185], v199 offset:18432
	ds_read_b128 v[186:189], v199 offset:19456
	ds_read_b128 v[190:193], v199 offset:20480
	ds_read_b128 v[202:205], v199 offset:21504
	ds_read_b128 v[208:211], v199 offset:22528
	ds_read_b128 v[212:215], v199 offset:23552
	global_load_lds_dwordx4 v[194:195], off
	v_lshl_add_u64 v[216:217], s[4:5], 0, v[166:167]
	s_mov_b32 m0, s22
	s_addc_u32 s57, s5, 0
	global_load_lds_dwordx4 v[216:217], off
	v_lshl_add_u64 v[218:219], s[56:57], 0, v[162:163]
	s_mov_b32 m0, s23
	v_lshl_add_u64 v[220:221], s[6:7], 0, v[164:165]
	global_load_lds_dwordx4 v[218:219], off
	v_lshl_add_u64 v[218:219], s[56:57], 0, v[166:167]
	s_mov_b32 m0, s87
	s_nop 0
	global_load_lds_dwordx4 v[218:219], off
	v_lshl_add_u64 v[218:219], s[6:7], 0, v[160:161]
	s_mov_b32 m0, s85
	s_nop 0
	global_load_lds_dwordx4 v[218:219], off
	s_mov_b32 m0, s33
	s_nop 0
	global_load_lds_dwordx4 v[220:221], off
	s_waitcnt vmcnt(8)
	s_waitcnt lgkmcnt(0)
	s_barrier
; #define PG8_STAGE(bufoff, gbase, voff) do { _Pragma("unroll") for (int _i = 0; _i < 2; ++_i) \
;         __builtin_amdgcn_global_load_lds((const unsigned*)((const char*)(gbase) + (voff)[_i]), (LAS unsigned*)(lds + (bufoff) + ldsw + _i * 8192), 16, 0, 0); } while (0)
; #define PG8_LDA(dst, b, h) do { _Pragma("unroll") for (int m = 0; m < 4; ++m) _Pragma("unroll") for (int k = 0; k < 2; ++k) dst[m][k] = *(const LAS bf16x8*)(lds + PG8_SA(b, h) + aoff + m * 2048 + k * 1024); } while (0)
; #define PG8_LDB(dst, b, h) do { _Pragma("unroll") for (int n = 0; n < 2; ++n) _Pragma("unroll") for (int k = 0; k < 2; ++k) dst[n][k] = *(const LAS bf16x8*)(lds + PG8_SB(b, h) + boff + n * 2048 + k * 1024); } while (0)
; #define PG8_MMA(ai, bj, At, Bt) do { __builtin_amdgcn_s_setprio(1); _Pragma("unroll") for (int m = 0; m < 4; ++m) _Pragma("unroll") for (int n = 0; n < 2; ++n) _Pragma("unroll") for (int k = 0; k < 2; ++k) \
;         acc[ai][bj][m][n] = __builtin_amdgcn_mfma_f32_16x16x32_bf16(Bt[n][k], At[m][k], acc[ai][bj][m][n], 0, 0, 0); __builtin_amdgcn_s_setprio(0); } while (0)
; #define PG8_WAIT_V(n) asm volatile("s_waitcnt vmcnt(" #n ")" ::: "memory")
; #define PG8_WAIT_L(n) asm volatile("s_waitcnt lgkmcnt(" #n ")" ::: "memory")
; #define PG8_BAR __builtin_amdgcn_s_barrier()
; #define PG8_SCHED __builtin_amdgcn_sched_barrier(0)
; template <class Epi, class Sched>
; DI void gemm_phase(LAS unsigned char* lds, const int K, const Sched& S, const Epi& E, const int wid) {
;     ...
;             PG8_WAIT_V(8); PG8_WAIT_L(0); PG8_BAR; PG8_MMA(1, 0, At, B0); PG8_MMA(1, 1, At, B1); PG8_BAR; PG8_SCHED;
;             PG8_LDB(B0, 1, 0); PG8_LDB(B1, 1, 1); PG8_SCHED; PG8_LDA(At, 1, 0); PG8_STAGE(PG8_SA(0, 1), a2 + hstep, voffA);
;             PG8_WAIT_V(8); PG8_WAIT_L(0); PG8_BAR; PG8_MMA(0, 0, At, B0); PG8_MMA(0, 1, At, B1); PG8_BAR; PG8_SCHED;
	s_waitcnt lgkmcnt(0)
	v_mfma_f32_16x16x32_bf16 v[92:95], v[96:99], v[174:177], v[92:95]
	v_mfma_f32_16x16x32_bf16 v[28:31], v[104:107], v[174:177], v[28:31]
	v_mfma_f32_16x16x32_bf16 v[84:87], v[96:99], v[182:185], v[84:87]
	v_mfma_f32_16x16x32_bf16 v[20:23], v[104:107], v[182:185], v[20:23]
	v_mfma_f32_16x16x32_bf16 v[80:83], v[96:99], v[190:193], v[80:83]
	v_mfma_f32_16x16x32_bf16 v[16:19], v[104:107], v[190:193], v[16:19]
	v_mfma_f32_16x16x32_bf16 v[88:91], v[96:99], v[208:211], v[88:91]
	v_mfma_f32_16x16x32_bf16 v[24:27], v[104:107], v[208:211], v[24:27]
	v_mfma_f32_16x16x32_bf16 v[92:95], v[100:103], v[178:181], v[92:95]
	v_mfma_f32_16x16x32_bf16 v[28:31], v[108:111], v[178:181], v[28:31]
	v_mfma_f32_16x16x32_bf16 v[84:87], v[100:103], v[186:189], v[84:87]
	v_mfma_f32_16x16x32_bf16 v[20:23], v[108:111], v[186:189], v[20:23]
	v_mfma_f32_16x16x32_bf16 v[80:83], v[100:103], v[202:205], v[80:83]
	v_mfma_f32_16x16x32_bf16 v[16:19], v[108:111], v[202:205], v[16:19]
	v_mfma_f32_16x16x32_bf16 v[88:91], v[100:103], v[212:215], v[88:91]
	v_mfma_f32_16x16x32_bf16 v[24:27], v[108:111], v[212:215], v[24:27]
	v_mfma_f32_16x16x32_bf16 v[76:79], v[112:115], v[174:177], v[76:79]
	v_mfma_f32_16x16x32_bf16 v[12:15], v[120:123], v[174:177], v[12:15]
	v_mfma_f32_16x16x32_bf16 v[68:71], v[112:115], v[182:185], v[68:71]
	v_mfma_f32_16x16x32_bf16 v[4:7], v[120:123], v[182:185], v[4:7]
	v_mfma_f32_16x16x32_bf16 v[64:67], v[112:115], v[190:193], v[64:67]
	v_mfma_f32_16x16x32_bf16 v[0:3], v[120:123], v[190:193], v[0:3]
	v_mfma_f32_16x16x32_bf16 v[72:75], v[112:115], v[208:211], v[72:75]
	v_mfma_f32_16x16x32_bf16 v[8:11], v[120:123], v[208:211], v[8:11]
	v_mfma_f32_16x16x32_bf16 v[76:79], v[116:119], v[178:181], v[76:79]
	v_mfma_f32_16x16x32_bf16 v[12:15], v[124:127], v[178:181], v[12:15]
	v_mfma_f32_16x16x32_bf16 v[68:71], v[116:119], v[186:189], v[68:71]
	v_mfma_f32_16x16x32_bf16 v[4:7], v[124:127], v[186:189], v[4:7]
	v_mfma_f32_16x16x32_bf16 v[64:67], v[116:119], v[202:205], v[64:67]
	v_mfma_f32_16x16x32_bf16 v[0:3], v[124:127], v[202:205], v[0:3]
	v_mfma_f32_16x16x32_bf16 v[72:75], v[116:119], v[212:215], v[72:75]
	v_mfma_f32_16x16x32_bf16 v[8:11], v[124:127], v[212:215], v[8:11]
	s_barrier
	v_add_u32_e32 v108, s96, v198
	v_add_u32_e32 v124, s90, v198
	ds_read_b128 v[96:99], v108
	ds_read_b128 v[100:103], v108 offset:1024
	ds_read_b128 v[104:107], v108 offset:2048
	ds_read_b128 v[108:111], v108 offset:3072
	ds_read_b128 v[112:115], v124
	ds_read_b128 v[116:119], v124 offset:1024
	ds_read_b128 v[120:123], v124 offset:2048
	ds_read_b128 v[124:127], v124 offset:3072
	s_add_u32 s6, s6, 0x80000
	s_addc_u32 s7, s7, 0
	s_mov_b32 m0, s29
	v_lshl_add_u64 v[222:223], s[6:7], 0, v[160:161]
	ds_read_b128 v[174:177], v199 offset:32768
	ds_read_b128 v[178:181], v199 offset:33792
	ds_read_b128 v[182:185], v199 offset:34816
	ds_read_b128 v[186:189], v199 offset:35840
	ds_read_b128 v[190:193], v199 offset:36864
	ds_read_b128 v[202:205], v199 offset:37888
	ds_read_b128 v[208:211], v199 offset:38912
	ds_read_b128 v[212:215], v199 offset:39936
	global_load_lds_dwordx4 v[222:223], off
	v_lshl_add_u64 v[222:223], s[6:7], 0, v[164:165]
	s_mov_b32 m0, s97
	s_nop 0
	global_load_lds_dwordx4 v[222:223], off
	s_waitcnt vmcnt(8)
	s_waitcnt lgkmcnt(0)
	s_barrier
	s_waitcnt lgkmcnt(0)
	v_mfma_f32_16x16x32_bf16 v[156:159], v[96:99], v[174:177], v[156:159]
	v_mfma_f32_16x16x32_bf16 v[60:63], v[104:107], v[174:177], v[60:63]
	v_mfma_f32_16x16x32_bf16 v[148:151], v[96:99], v[182:185], v[148:151]
	v_mfma_f32_16x16x32_bf16 v[52:55], v[104:107], v[182:185], v[52:55]
	v_mfma_f32_16x16x32_bf16 v[144:147], v[96:99], v[190:193], v[144:147]
	v_mfma_f32_16x16x32_bf16 v[48:51], v[104:107], v[190:193], v[48:51]
	v_mfma_f32_16x16x32_bf16 v[152:155], v[96:99], v[208:211], v[152:155]
	v_mfma_f32_16x16x32_bf16 v[56:59], v[104:107], v[208:211], v[56:59]
	v_mfma_f32_16x16x32_bf16 v[156:159], v[100:103], v[178:181], v[156:159]
	v_mfma_f32_16x16x32_bf16 v[60:63], v[108:111], v[178:181], v[60:63]
	v_mfma_f32_16x16x32_bf16 v[148:151], v[100:103], v[186:189], v[148:151]
	v_mfma_f32_16x16x32_bf16 v[52:55], v[108:111], v[186:189], v[52:55]
	v_mfma_f32_16x16x32_bf16 v[144:147], v[100:103], v[202:205], v[144:147]
	v_mfma_f32_16x16x32_bf16 v[48:51], v[108:111], v[202:205], v[48:51]
	v_mfma_f32_16x16x32_bf16 v[152:155], v[100:103], v[212:215], v[152:155]
	v_mfma_f32_16x16x32_bf16 v[56:59], v[108:111], v[212:215], v[56:59]
	v_mfma_f32_16x16x32_bf16 v[140:143], v[112:115], v[174:177], v[140:143]
	v_mfma_f32_16x16x32_bf16 v[44:47], v[120:123], v[174:177], v[44:47]
	v_mfma_f32_16x16x32_bf16 v[132:135], v[112:115], v[182:185], v[132:135]
	v_mfma_f32_16x16x32_bf16 v[36:39], v[120:123], v[182:185], v[36:39]
	v_mfma_f32_16x16x32_bf16 v[128:131], v[112:115], v[190:193], v[128:131]
	v_mfma_f32_16x16x32_bf16 v[32:35], v[120:123], v[190:193], v[32:35]
	v_mfma_f32_16x16x32_bf16 v[136:139], v[112:115], v[208:211], v[136:139]
	v_mfma_f32_16x16x32_bf16 v[40:43], v[120:123], v[208:211], v[40:43]
	v_mfma_f32_16x16x32_bf16 v[140:143], v[116:119], v[178:181], v[140:143]
	v_mfma_f32_16x16x32_bf16 v[44:47], v[124:127], v[178:181], v[44:47]
	v_mfma_f32_16x16x32_bf16 v[132:135], v[116:119], v[186:189], v[132:135]
	v_mfma_f32_16x16x32_bf16 v[36:39], v[124:127], v[186:189], v[36:39]
	v_mfma_f32_16x16x32_bf16 v[128:131], v[116:119], v[202:205], v[128:131]
	v_mfma_f32_16x16x32_bf16 v[32:35], v[124:127], v[202:205], v[32:35]
	v_mfma_f32_16x16x32_bf16 v[136:139], v[116:119], v[212:215], v[136:139]
	v_mfma_f32_16x16x32_bf16 v[40:43], v[124:127], v[212:215], v[40:43]
	s_barrier
; #define PG8_STAGE(bufoff, gbase, voff) do { _Pragma("unroll") for (int _i = 0; _i < 2; ++_i) \
;         __builtin_amdgcn_global_load_lds((const unsigned*)((const char*)(gbase) + (voff)[_i]), (LAS unsigned*)(lds + (bufoff) + ldsw + _i * 8192), 16, 0, 0); } while (0)
; #define PG8_LDA(dst, b, h) do { _Pragma("unroll") for (int m = 0; m < 4; ++m) _Pragma("unroll") for (int k = 0; k < 2; ++k) dst[m][k] = *(const LAS bf16x8*)(lds + PG8_SA(b, h) + aoff + m * 2048 + k * 1024); } while (0)
; #define PG8_MMA(ai, bj, At, Bt) do { __builtin_amdgcn_s_setprio(1); _Pragma("unroll") for (int m = 0; m < 4; ++m) _Pragma("unroll") for (int n = 0; n < 2; ++n) _Pragma("unroll") for (int k = 0; k < 2; ++k) \
;         acc[ai][bj][m][n] = __builtin_amdgcn_mfma_f32_16x16x32_bf16(Bt[n][k], At[m][k], acc[ai][bj][m][n], 0, 0, 0); __builtin_amdgcn_s_setprio(0); } while (0)
; #define PG8_WAIT_V(n) asm volatile("s_waitcnt vmcnt(" #n ")" ::: "memory")
; #define PG8_WAIT_L(n) asm volatile("s_waitcnt lgkmcnt(" #n ")" ::: "memory")
; #define PG8_BAR __builtin_amdgcn_s_barrier()
; #define PG8_SCHED __builtin_amdgcn_sched_barrier(0)
; template <class Epi, class Sched>
; DI void gemm_phase(LAS unsigned char* lds, const int K, const Sched& S, const Epi& E, const int wid) {
;     ...
;             PG8_LDA(At, 1, 1); PG8_STAGE(PG8_SB(1, 0), b3, voffB); PG8_STAGE(PG8_SB(1, 1), b3 + hstep, voffB); PG8_STAGE(PG8_SA(1, 0), a3, voffA);
;             PG8_WAIT_V(8); PG8_WAIT_L(0); PG8_BAR; PG8_MMA(1, 0, At, B0); PG8_MMA(1, 1, At, B1); PG8_BAR; PG8_SCHED;
;         }
	s_mov_b32 m0, s94
	v_lshl_add_u64 v[194:195], v[194:195], 0, s[18:19]
	s_add_u32 s4, s4, 0x80080
	ds_read_b128 v[174:177], v199 offset:49152
	ds_read_b128 v[178:181], v199 offset:50176
	ds_read_b128 v[182:185], v199 offset:51200
	ds_read_b128 v[186:189], v199 offset:52224
	ds_read_b128 v[190:193], v199 offset:53248
	ds_read_b128 v[202:205], v199 offset:54272
	ds_read_b128 v[208:211], v199 offset:55296
	ds_read_b128 v[212:215], v199 offset:56320
	global_load_lds_dwordx4 v[194:195], off
	v_lshl_add_u64 v[194:195], v[216:217], 0, s[18:19]
	s_mov_b32 m0, s84
	s_addc_u32 s5, s5, 0
	global_load_lds_dwordx4 v[194:195], off
	v_lshl_add_u64 v[194:195], s[4:5], 0, v[162:163]
	s_mov_b32 m0, s86
	s_nop 0
	global_load_lds_dwordx4 v[194:195], off
	v_lshl_add_u64 v[194:195], s[4:5], 0, v[166:167]
	s_mov_b32 m0, s28
	s_nop 0
	global_load_lds_dwordx4 v[194:195], off
	v_lshl_add_u64 v[194:195], v[218:219], 0, s[18:19]
	s_mov_b32 m0, s91
	s_nop 0
	global_load_lds_dwordx4 v[194:195], off
	v_lshl_add_u64 v[194:195], v[220:221], 0, s[18:19]
	s_mov_b32 m0, s88
	s_nop 0
	global_load_lds_dwordx4 v[194:195], off
	s_waitcnt vmcnt(8)
	s_waitcnt lgkmcnt(0)
	s_barrier
	s_waitcnt lgkmcnt(0)
	v_mfma_f32_16x16x32_bf16 v[92:95], v[96:99], v[174:177], v[92:95]
	v_mfma_f32_16x16x32_bf16 v[28:31], v[104:107], v[174:177], v[28:31]
	v_mfma_f32_16x16x32_bf16 v[84:87], v[96:99], v[182:185], v[84:87]
	v_mfma_f32_16x16x32_bf16 v[20:23], v[104:107], v[182:185], v[20:23]
	v_mfma_f32_16x16x32_bf16 v[80:83], v[96:99], v[190:193], v[80:83]
	v_mfma_f32_16x16x32_bf16 v[16:19], v[104:107], v[190:193], v[16:19]
	v_mfma_f32_16x16x32_bf16 v[88:91], v[96:99], v[208:211], v[88:91]
	v_mfma_f32_16x16x32_bf16 v[24:27], v[104:107], v[208:211], v[24:27]
	v_mfma_f32_16x16x32_bf16 v[92:95], v[100:103], v[178:181], v[92:95]
	v_mfma_f32_16x16x32_bf16 v[28:31], v[108:111], v[178:181], v[28:31]
	v_mfma_f32_16x16x32_bf16 v[84:87], v[100:103], v[186:189], v[84:87]
	v_mfma_f32_16x16x32_bf16 v[20:23], v[108:111], v[186:189], v[20:23]
	v_mfma_f32_16x16x32_bf16 v[80:83], v[100:103], v[202:205], v[80:83]
	v_mfma_f32_16x16x32_bf16 v[16:19], v[108:111], v[202:205], v[16:19]
	v_mfma_f32_16x16x32_bf16 v[88:91], v[100:103], v[212:215], v[88:91]
	v_mfma_f32_16x16x32_bf16 v[24:27], v[108:111], v[212:215], v[24:27]
	v_mfma_f32_16x16x32_bf16 v[76:79], v[112:115], v[174:177], v[76:79]
	v_mfma_f32_16x16x32_bf16 v[12:15], v[120:123], v[174:177], v[12:15]
	v_mfma_f32_16x16x32_bf16 v[68:71], v[112:115], v[182:185], v[68:71]
	v_mfma_f32_16x16x32_bf16 v[4:7], v[120:123], v[182:185], v[4:7]
	v_mfma_f32_16x16x32_bf16 v[64:67], v[112:115], v[190:193], v[64:67]
	v_mfma_f32_16x16x32_bf16 v[0:3], v[120:123], v[190:193], v[0:3]
	v_mfma_f32_16x16x32_bf16 v[72:75], v[112:115], v[208:211], v[72:75]
	v_mfma_f32_16x16x32_bf16 v[8:11], v[120:123], v[208:211], v[8:11]
	v_mfma_f32_16x16x32_bf16 v[76:79], v[116:119], v[178:181], v[76:79]
	v_mfma_f32_16x16x32_bf16 v[12:15], v[124:127], v[178:181], v[12:15]
	v_mfma_f32_16x16x32_bf16 v[68:71], v[116:119], v[186:189], v[68:71]
	v_mfma_f32_16x16x32_bf16 v[4:7], v[124:127], v[186:189], v[4:7]
	v_mfma_f32_16x16x32_bf16 v[64:67], v[116:119], v[202:205], v[64:67]
	v_mfma_f32_16x16x32_bf16 v[0:3], v[124:127], v[202:205], v[0:3]
	v_mfma_f32_16x16x32_bf16 v[72:75], v[116:119], v[212:215], v[72:75]
	v_mfma_f32_16x16x32_bf16 v[8:11], v[124:127], v[212:215], v[8:11]
	s_barrier
	s_cmp_gt_u32 s54, 29
	s_mov_b32 s54, s8
	s_cbranch_scc1 .LBB0_818

; #define PG8_STAGE(bufoff, gbase, voff) do { _Pragma("unroll") for (int _i = 0; _i < 2; ++_i) \
;         __builtin_amdgcn_global_load_lds((const unsigned*)((const char*)(gbase) + (voff)[_i]), (LAS unsigned*)(lds + (bufoff) + ldsw + _i * 8192), 16, 0, 0); } while (0)
; #define PG8_LDA(dst, b, h) do { _Pragma("unroll") for (int m = 0; m < 4; ++m) _Pragma("unroll") for (int k = 0; k < 2; ++k) dst[m][k] = *(const LAS bf16x8*)(lds + PG8_SA(b, h) + aoff + m * 2048 + k * 1024); } while (0)
; #define PG8_LDB(dst, b, h) do { _Pragma("unroll") for (int n = 0; n < 2; ++n) _Pragma("unroll") for (int k = 0; k < 2; ++k) dst[n][k] = *(const LAS bf16x8*)(lds + PG8_SB(b, h) + boff + n * 2048 + k * 1024); } while (0)
; #define PG8_MMA(ai, bj, At, Bt) do { __builtin_amdgcn_s_setprio(1); _Pragma("unroll") for (int m = 0; m < 4; ++m) _Pragma("unroll") for (int n = 0; n < 2; ++n) _Pragma("unroll") for (int k = 0; k < 2; ++k) \
;         acc[ai][bj][m][n] = __builtin_amdgcn_mfma_f32_16x16x32_bf16(Bt[n][k], At[m][k], acc[ai][bj][m][n], 0, 0, 0); __builtin_amdgcn_s_setprio(0); } while (0)
; #define PG8_WAIT_V(n) asm volatile("s_waitcnt vmcnt(" #n ")" ::: "memory")
; #define PG8_WAIT_L(n) asm volatile("s_waitcnt lgkmcnt(" #n ")" ::: "memory")
; #define PG8_BAR __builtin_amdgcn_s_barrier()
; #define PG8_SCHED __builtin_amdgcn_sched_barrier(0)
;     DI void a_ready(const Unit& u) const { if (ctr && u.pm >= 128) wait_counter(ctr, target); }
; template <class Epi, class Sched>
; DI void gemm_phase(LAS unsigned char* lds, const int K, const Sched& S, const Epi& E, const int wid) {
;     ...
;         for (int t = 0; t < nt; t += 2) {
;             const bool last = (t == nt - 2);
;             const char* a1 = cA + (size_t)(t + 1) * kstep;
;             const char* a2 = last ? nA : cA + (size_t)(t + 2) * kstep; const char* b2 = last ? nB : cB + (size_t)(t + 2) * kstep;
;             const char* a3 = a2 + kstep; const char* b3 = b2 + kstep;
;             if (last && has_next) S.a_ready(nxt);
;             PG8_LDB(B0, 0, 0); PG8_LDB(B1, 0, 1); PG8_SCHED; PG8_LDA(At, 0, 0); PG8_STAGE(PG8_SA(1, 1), a1 + hstep, voffA);
;             PG8_WAIT_V(8); PG8_WAIT_L(0); PG8_BAR; PG8_MMA(0, 0, At, B0); PG8_MMA(0, 1, At, B1); PG8_BAR; PG8_SCHED;
;             PG8_LDA(At, 0, 1); PG8_STAGE(PG8_SB(0, 0), b2, voffB); PG8_STAGE(PG8_SB(0, 1), b2 + hstep, voffB); PG8_STAGE(PG8_SA(0, 0), a2, voffA);
.LBB0_1068:
	ds_read_b128 v[128:131], v179
	ds_read_b128 v[132:135], v179 offset:1024
	ds_read_b128 v[136:139], v179 offset:2048
	ds_read_b128 v[140:143], v179 offset:3072
	ds_read_b128 v[144:147], v180
	ds_read_b128 v[160:163], v180 offset:1024
	ds_read_b128 v[164:167], v180 offset:2048
	ds_read_b128 v[168:171], v180 offset:3072
	s_add_i32 s38, s6, 2
	s_add_u32 s4, s18, 0x100
	s_addc_u32 s5, s19, 0
	s_cmp_eq_u32 s35, s6
	s_cselect_b32 s6, s16, s36
	s_cselect_b32 s21, s15, s5
	s_cselect_b32 s20, s14, s4
	s_cselect_b32 s7, s17, s37
	s_mov_b32 m0, s89
	v_lshl_add_u64 v[212:213], s[18:19], 0, v[156:157]
	ds_read_b128 v[172:175], v181
	ds_read_b128 v[182:185], v181 offset:1024
	ds_read_b128 v[186:189], v181 offset:2048
	ds_read_b128 v[190:193], v181 offset:3072
	ds_read_b128 v[194:197], v181 offset:4096
	ds_read_b128 v[198:201], v181 offset:5120
	ds_read_b128 v[202:205], v181 offset:6144
	ds_read_b128 v[208:211], v181 offset:7168
	global_load_lds_dwordx4 v[212:213], off
	v_lshl_add_u64 v[212:213], s[18:19], 0, v[158:159]
	s_mov_b32 m0, s26
	s_nop 0
	global_load_lds_dwordx4 v[212:213], off
	s_waitcnt vmcnt(8)
	s_waitcnt lgkmcnt(0)
	s_barrier
	s_waitcnt lgkmcnt(0)
	v_mfma_f32_16x16x32_bf16 v[124:127], v[128:131], v[172:175], v[124:127]
	v_mfma_f32_16x16x32_bf16 v[120:123], v[136:139], v[172:175], v[120:123]
	v_mfma_f32_16x16x32_bf16 v[116:119], v[128:131], v[186:189], v[116:119]
	v_mfma_f32_16x16x32_bf16 v[112:115], v[136:139], v[186:189], v[112:115]
	v_mfma_f32_16x16x32_bf16 v[100:103], v[128:131], v[194:197], v[100:103]
	v_mfma_f32_16x16x32_bf16 v[96:99], v[136:139], v[194:197], v[96:99]
	v_mfma_f32_16x16x32_bf16 v[84:87], v[128:131], v[202:205], v[84:87]
	v_mfma_f32_16x16x32_bf16 v[80:83], v[136:139], v[202:205], v[80:83]
	v_mfma_f32_16x16x32_bf16 v[124:127], v[132:135], v[182:185], v[124:127]
	v_mfma_f32_16x16x32_bf16 v[120:123], v[140:143], v[182:185], v[120:123]
	v_mfma_f32_16x16x32_bf16 v[116:119], v[132:135], v[190:193], v[116:119]
	v_mfma_f32_16x16x32_bf16 v[112:115], v[140:143], v[190:193], v[112:115]
	v_mfma_f32_16x16x32_bf16 v[100:103], v[132:135], v[198:201], v[100:103]
	v_mfma_f32_16x16x32_bf16 v[96:99], v[140:143], v[198:201], v[96:99]
	v_mfma_f32_16x16x32_bf16 v[84:87], v[132:135], v[208:211], v[84:87]
	v_mfma_f32_16x16x32_bf16 v[80:83], v[140:143], v[208:211], v[80:83]
	v_mfma_f32_16x16x32_bf16 v[108:111], v[144:147], v[172:175], v[108:111]
	v_mfma_f32_16x16x32_bf16 v[104:107], v[164:167], v[172:175], v[104:107]
	v_mfma_f32_16x16x32_bf16 v[92:95], v[144:147], v[186:189], v[92:95]
	v_mfma_f32_16x16x32_bf16 v[88:91], v[164:167], v[186:189], v[88:91]
	v_mfma_f32_16x16x32_bf16 v[76:79], v[144:147], v[194:197], v[76:79]
	v_mfma_f32_16x16x32_bf16 v[72:75], v[164:167], v[194:197], v[72:75]
	v_mfma_f32_16x16x32_bf16 v[68:71], v[144:147], v[202:205], v[68:71]
	v_mfma_f32_16x16x32_bf16 v[64:67], v[164:167], v[202:205], v[64:67]
	v_mfma_f32_16x16x32_bf16 v[108:111], v[160:163], v[182:185], v[108:111]
	v_mfma_f32_16x16x32_bf16 v[104:107], v[168:171], v[182:185], v[104:107]
	v_mfma_f32_16x16x32_bf16 v[92:95], v[160:163], v[190:193], v[92:95]
	v_mfma_f32_16x16x32_bf16 v[88:91], v[168:171], v[190:193], v[88:91]
	v_mfma_f32_16x16x32_bf16 v[76:79], v[160:163], v[198:201], v[76:79]
	v_mfma_f32_16x16x32_bf16 v[72:75], v[168:171], v[198:201], v[72:75]
	v_mfma_f32_16x16x32_bf16 v[68:71], v[160:163], v[208:211], v[68:71]
	v_mfma_f32_16x16x32_bf16 v[64:67], v[168:171], v[208:211], v[64:67]
	s_barrier
	s_mov_b32 m0, s27
	v_lshl_add_u64 v[212:213], s[6:7], 0, v[150:151]
	s_add_u32 s18, s6, 0x164000
	ds_read_b128 v[172:175], v181 offset:16384
	ds_read_b128 v[182:185], v181 offset:17408
	ds_read_b128 v[186:189], v181 offset:18432
	ds_read_b128 v[190:193], v181 offset:19456
	ds_read_b128 v[194:197], v181 offset:20480
	ds_read_b128 v[198:201], v181 offset:21504
	ds_read_b128 v[202:205], v181 offset:22528
	ds_read_b128 v[208:211], v181 offset:23552
	global_load_lds_dwordx4 v[212:213], off
	v_lshl_add_u64 v[214:215], s[6:7], 0, v[154:155]
	s_mov_b32 m0, s22
	s_addc_u32 s19, s7, 0
	global_load_lds_dwordx4 v[214:215], off
	v_lshl_add_u64 v[216:217], s[18:19], 0, v[150:151]
	s_mov_b32 m0, s23
	v_lshl_add_u64 v[218:219], s[20:21], 0, v[152:153]
	global_load_lds_dwordx4 v[216:217], off
	v_lshl_add_u64 v[216:217], s[18:19], 0, v[154:155]
	s_mov_b32 m0, s87
	s_nop 0
	global_load_lds_dwordx4 v[216:217], off
	v_lshl_add_u64 v[216:217], s[20:21], 0, v[148:149]
	s_mov_b32 m0, s85
	s_nop 0
	global_load_lds_dwordx4 v[216:217], off
	s_mov_b32 m0, s33
	s_nop 0
	global_load_lds_dwordx4 v[218:219], off
	s_waitcnt vmcnt(8)
	s_waitcnt lgkmcnt(0)
	s_barrier
; #define PG8_STAGE(bufoff, gbase, voff) do { _Pragma("unroll") for (int _i = 0; _i < 2; ++_i) \
;         __builtin_amdgcn_global_load_lds((const unsigned*)((const char*)(gbase) + (voff)[_i]), (LAS unsigned*)(lds + (bufoff) + ldsw + _i * 8192), 16, 0, 0); } while (0)
; #define PG8_LDA(dst, b, h) do { _Pragma("unroll") for (int m = 0; m < 4; ++m) _Pragma("unroll") for (int k = 0; k < 2; ++k) dst[m][k] = *(const LAS bf16x8*)(lds + PG8_SA(b, h) + aoff + m * 2048 + k * 1024); } while (0)
; #define PG8_LDB(dst, b, h) do { _Pragma("unroll") for (int n = 0; n < 2; ++n) _Pragma("unroll") for (int k = 0; k < 2; ++k) dst[n][k] = *(const LAS bf16x8*)(lds + PG8_SB(b, h) + boff + n * 2048 + k * 1024); } while (0)
; #define PG8_MMA(ai, bj, At, Bt) do { __builtin_amdgcn_s_setprio(1); _Pragma("unroll") for (int m = 0; m < 4; ++m) _Pragma("unroll") for (int n = 0; n < 2; ++n) _Pragma("unroll") for (int k = 0; k < 2; ++k) \
;         acc[ai][bj][m][n] = __builtin_amdgcn_mfma_f32_16x16x32_bf16(Bt[n][k], At[m][k], acc[ai][bj][m][n], 0, 0, 0); __builtin_amdgcn_s_setprio(0); } while (0)
; #define PG8_WAIT_V(n) asm volatile("s_waitcnt vmcnt(" #n ")" ::: "memory")
; #define PG8_WAIT_L(n) asm volatile("s_waitcnt lgkmcnt(" #n ")" ::: "memory")
; #define PG8_BAR __builtin_amdgcn_s_barrier()
; #define PG8_SCHED __builtin_amdgcn_sched_barrier(0)
; template <class Epi, class Sched>
; DI void gemm_phase(LAS unsigned char* lds, const int K, const Sched& S, const Epi& E, const int wid) {
;     ...
;             PG8_WAIT_V(8); PG8_WAIT_L(0); PG8_BAR; PG8_MMA(1, 0, At, B0); PG8_MMA(1, 1, At, B1); PG8_BAR; PG8_SCHED;
;             PG8_LDB(B0, 1, 0); PG8_LDB(B1, 1, 1); PG8_SCHED; PG8_LDA(At, 1, 0); PG8_STAGE(PG8_SA(0, 1), a2 + hstep, voffA);
;             PG8_WAIT_V(8); PG8_WAIT_L(0); PG8_BAR; PG8_MMA(0, 0, At, B0); PG8_MMA(0, 1, At, B1); PG8_BAR; PG8_SCHED;
	s_waitcnt lgkmcnt(0)
	v_mfma_f32_16x16x32_bf16 v[60:63], v[128:131], v[172:175], v[60:63]
	v_mfma_f32_16x16x32_bf16 v[56:59], v[136:139], v[172:175], v[56:59]
	v_mfma_f32_16x16x32_bf16 v[52:55], v[128:131], v[186:189], v[52:55]
	v_mfma_f32_16x16x32_bf16 v[48:51], v[136:139], v[186:189], v[48:51]
	v_mfma_f32_16x16x32_bf16 v[36:39], v[128:131], v[194:197], v[36:39]
	v_mfma_f32_16x16x32_bf16 v[32:35], v[136:139], v[194:197], v[32:35]
	v_mfma_f32_16x16x32_bf16 v[20:23], v[128:131], v[202:205], v[20:23]
	v_mfma_f32_16x16x32_bf16 v[16:19], v[136:139], v[202:205], v[16:19]
	v_mfma_f32_16x16x32_bf16 v[60:63], v[132:135], v[182:185], v[60:63]
	v_mfma_f32_16x16x32_bf16 v[56:59], v[140:143], v[182:185], v[56:59]
	v_mfma_f32_16x16x32_bf16 v[52:55], v[132:135], v[190:193], v[52:55]
	v_mfma_f32_16x16x32_bf16 v[48:51], v[140:143], v[190:193], v[48:51]
	v_mfma_f32_16x16x32_bf16 v[36:39], v[132:135], v[198:201], v[36:39]
	v_mfma_f32_16x16x32_bf16 v[32:35], v[140:143], v[198:201], v[32:35]
	v_mfma_f32_16x16x32_bf16 v[20:23], v[132:135], v[208:211], v[20:23]
	v_mfma_f32_16x16x32_bf16 v[16:19], v[140:143], v[208:211], v[16:19]
	v_mfma_f32_16x16x32_bf16 v[44:47], v[144:147], v[172:175], v[44:47]
	v_mfma_f32_16x16x32_bf16 v[40:43], v[164:167], v[172:175], v[40:43]
	v_mfma_f32_16x16x32_bf16 v[28:31], v[144:147], v[186:189], v[28:31]
	v_mfma_f32_16x16x32_bf16 v[24:27], v[164:167], v[186:189], v[24:27]
	v_mfma_f32_16x16x32_bf16 v[12:15], v[144:147], v[194:197], v[12:15]
	v_mfma_f32_16x16x32_bf16 v[8:11], v[164:167], v[194:197], v[8:11]
	v_mfma_f32_16x16x32_bf16 v[4:7], v[144:147], v[202:205], v[4:7]
	v_mfma_f32_16x16x32_bf16 v[0:3], v[164:167], v[202:205], v[0:3]
	v_mfma_f32_16x16x32_bf16 v[44:47], v[160:163], v[182:185], v[44:47]
	v_mfma_f32_16x16x32_bf16 v[40:43], v[168:171], v[182:185], v[40:43]
	v_mfma_f32_16x16x32_bf16 v[28:31], v[160:163], v[190:193], v[28:31]
	v_mfma_f32_16x16x32_bf16 v[24:27], v[168:171], v[190:193], v[24:27]
	v_mfma_f32_16x16x32_bf16 v[12:15], v[160:163], v[198:201], v[12:15]
	v_mfma_f32_16x16x32_bf16 v[8:11], v[168:171], v[198:201], v[8:11]
	v_mfma_f32_16x16x32_bf16 v[4:7], v[160:163], v[208:211], v[4:7]
	v_mfma_f32_16x16x32_bf16 v[0:3], v[168:171], v[208:211], v[0:3]
	s_barrier
	v_add_u32_e32 v140, s96, v177
	v_add_u32_e32 v168, s90, v177
	ds_read_b128 v[128:131], v140
	ds_read_b128 v[132:135], v140 offset:1024
	ds_read_b128 v[136:139], v140 offset:2048
	ds_read_b128 v[140:143], v140 offset:3072
	ds_read_b128 v[144:147], v168
	ds_read_b128 v[160:163], v168 offset:1024
	ds_read_b128 v[164:167], v168 offset:2048
	ds_read_b128 v[168:171], v168 offset:3072
	s_add_u32 s18, s20, 0x164000
	s_addc_u32 s19, s21, 0
	s_mov_b32 m0, s29
	v_lshl_add_u64 v[220:221], s[18:19], 0, v[148:149]
	ds_read_b128 v[172:175], v181 offset:32768
	ds_read_b128 v[182:185], v181 offset:33792
	ds_read_b128 v[186:189], v181 offset:34816
	ds_read_b128 v[190:193], v181 offset:35840
	ds_read_b128 v[194:197], v181 offset:36864
	ds_read_b128 v[198:201], v181 offset:37888
	ds_read_b128 v[202:205], v181 offset:38912
	ds_read_b128 v[208:211], v181 offset:39936
	global_load_lds_dwordx4 v[220:221], off
	v_lshl_add_u64 v[220:221], s[18:19], 0, v[152:153]
	s_mov_b32 m0, s97
	s_nop 0
	global_load_lds_dwordx4 v[220:221], off
	s_waitcnt vmcnt(8)
	s_waitcnt lgkmcnt(0)
	s_barrier
	s_waitcnt lgkmcnt(0)
	v_mfma_f32_16x16x32_bf16 v[124:127], v[128:131], v[172:175], v[124:127]
	v_mfma_f32_16x16x32_bf16 v[120:123], v[136:139], v[172:175], v[120:123]
	v_mfma_f32_16x16x32_bf16 v[116:119], v[128:131], v[186:189], v[116:119]
	v_mfma_f32_16x16x32_bf16 v[112:115], v[136:139], v[186:189], v[112:115]
	v_mfma_f32_16x16x32_bf16 v[100:103], v[128:131], v[194:197], v[100:103]
	v_mfma_f32_16x16x32_bf16 v[96:99], v[136:139], v[194:197], v[96:99]
	v_mfma_f32_16x16x32_bf16 v[84:87], v[128:131], v[202:205], v[84:87]
	v_mfma_f32_16x16x32_bf16 v[80:83], v[136:139], v[202:205], v[80:83]
	v_mfma_f32_16x16x32_bf16 v[124:127], v[132:135], v[182:185], v[124:127]
	v_mfma_f32_16x16x32_bf16 v[120:123], v[140:143], v[182:185], v[120:123]
	v_mfma_f32_16x16x32_bf16 v[116:119], v[132:135], v[190:193], v[116:119]
	v_mfma_f32_16x16x32_bf16 v[112:115], v[140:143], v[190:193], v[112:115]
	v_mfma_f32_16x16x32_bf16 v[100:103], v[132:135], v[198:201], v[100:103]
	v_mfma_f32_16x16x32_bf16 v[96:99], v[140:143], v[198:201], v[96:99]
	v_mfma_f32_16x16x32_bf16 v[84:87], v[132:135], v[208:211], v[84:87]
	v_mfma_f32_16x16x32_bf16 v[80:83], v[140:143], v[208:211], v[80:83]
	v_mfma_f32_16x16x32_bf16 v[108:111], v[144:147], v[172:175], v[108:111]
	v_mfma_f32_16x16x32_bf16 v[104:107], v[164:167], v[172:175], v[104:107]
	v_mfma_f32_16x16x32_bf16 v[92:95], v[144:147], v[186:189], v[92:95]
	v_mfma_f32_16x16x32_bf16 v[88:91], v[164:167], v[186:189], v[88:91]
	v_mfma_f32_16x16x32_bf16 v[76:79], v[144:147], v[194:197], v[76:79]
	v_mfma_f32_16x16x32_bf16 v[72:75], v[164:167], v[194:197], v[72:75]
	v_mfma_f32_16x16x32_bf16 v[68:71], v[144:147], v[202:205], v[68:71]
	v_mfma_f32_16x16x32_bf16 v[64:67], v[164:167], v[202:205], v[64:67]
	v_mfma_f32_16x16x32_bf16 v[108:111], v[160:163], v[182:185], v[108:111]
	v_mfma_f32_16x16x32_bf16 v[104:107], v[168:171], v[182:185], v[104:107]
	v_mfma_f32_16x16x32_bf16 v[92:95], v[160:163], v[190:193], v[92:95]
	v_mfma_f32_16x16x32_bf16 v[88:91], v[168:171], v[190:193], v[88:91]
	v_mfma_f32_16x16x32_bf16 v[76:79], v[160:163], v[198:201], v[76:79]
	v_mfma_f32_16x16x32_bf16 v[72:75], v[168:171], v[198:201], v[72:75]
	v_mfma_f32_16x16x32_bf16 v[68:71], v[160:163], v[208:211], v[68:71]
	v_mfma_f32_16x16x32_bf16 v[64:67], v[168:171], v[208:211], v[64:67]
	s_barrier
; #define PG8_STAGE(bufoff, gbase, voff) do { _Pragma("unroll") for (int _i = 0; _i < 2; ++_i) \
;         __builtin_amdgcn_global_load_lds((const unsigned*)((const char*)(gbase) + (voff)[_i]), (LAS unsigned*)(lds + (bufoff) + ldsw + _i * 8192), 16, 0, 0); } while (0)
; #define PG8_LDA(dst, b, h) do { _Pragma("unroll") for (int m = 0; m < 4; ++m) _Pragma("unroll") for (int k = 0; k < 2; ++k) dst[m][k] = *(const LAS bf16x8*)(lds + PG8_SA(b, h) + aoff + m * 2048 + k * 1024); } while (0)
; #define PG8_MMA(ai, bj, At, Bt) do { __builtin_amdgcn_s_setprio(1); _Pragma("unroll") for (int m = 0; m < 4; ++m) _Pragma("unroll") for (int n = 0; n < 2; ++n) _Pragma("unroll") for (int k = 0; k < 2; ++k) \
;         acc[ai][bj][m][n] = __builtin_amdgcn_mfma_f32_16x16x32_bf16(Bt[n][k], At[m][k], acc[ai][bj][m][n], 0, 0, 0); __builtin_amdgcn_s_setprio(0); } while (0)
; #define PG8_WAIT_V(n) asm volatile("s_waitcnt vmcnt(" #n ")" ::: "memory")
; #define PG8_WAIT_L(n) asm volatile("s_waitcnt lgkmcnt(" #n ")" ::: "memory")
; #define PG8_BAR __builtin_amdgcn_s_barrier()
; #define PG8_SCHED __builtin_amdgcn_sched_barrier(0)
; template <class Epi, class Sched>
; DI void gemm_phase(LAS unsigned char* lds, const int K, const Sched& S, const Epi& E, const int wid) {
;     ...
;             PG8_LDA(At, 1, 1); PG8_STAGE(PG8_SB(1, 0), b3, voffB); PG8_STAGE(PG8_SB(1, 1), b3 + hstep, voffB); PG8_STAGE(PG8_SA(1, 0), a3, voffA);
;             PG8_WAIT_V(8); PG8_WAIT_L(0); PG8_BAR; PG8_MMA(1, 0, At, B0); PG8_MMA(1, 1, At, B1); PG8_BAR; PG8_SCHED;
;         }
	s_mov_b32 m0, s94
	v_lshl_add_u64 v[212:213], v[212:213], 0, s[10:11]
	s_add_u32 s6, s6, 0x164080
	ds_read_b128 v[172:175], v181 offset:49152
	ds_read_b128 v[182:185], v181 offset:50176
	ds_read_b128 v[186:189], v181 offset:51200
	ds_read_b128 v[190:193], v181 offset:52224
	ds_read_b128 v[194:197], v181 offset:53248
	ds_read_b128 v[198:201], v181 offset:54272
	ds_read_b128 v[202:205], v181 offset:55296
	ds_read_b128 v[208:211], v181 offset:56320
	global_load_lds_dwordx4 v[212:213], off
	v_lshl_add_u64 v[212:213], v[214:215], 0, s[10:11]
	s_mov_b32 m0, s84
	s_addc_u32 s7, s7, 0
	global_load_lds_dwordx4 v[212:213], off
	v_lshl_add_u64 v[212:213], s[6:7], 0, v[150:151]
	s_mov_b32 m0, s86
	s_nop 0
	global_load_lds_dwordx4 v[212:213], off
	v_lshl_add_u64 v[212:213], s[6:7], 0, v[154:155]
	s_mov_b32 m0, s28
	s_nop 0
	global_load_lds_dwordx4 v[212:213], off
	v_lshl_add_u64 v[212:213], v[216:217], 0, s[10:11]
	s_mov_b32 m0, s91
	s_nop 0
	global_load_lds_dwordx4 v[212:213], off
	v_lshl_add_u64 v[212:213], v[218:219], 0, s[10:11]
	s_mov_b32 m0, s88
	s_nop 0
	global_load_lds_dwordx4 v[212:213], off
	s_waitcnt vmcnt(8)
	s_waitcnt lgkmcnt(0)
	s_barrier
	s_waitcnt lgkmcnt(0)
	v_mfma_f32_16x16x32_bf16 v[60:63], v[128:131], v[172:175], v[60:63]
	v_mfma_f32_16x16x32_bf16 v[56:59], v[136:139], v[172:175], v[56:59]
	v_mfma_f32_16x16x32_bf16 v[52:55], v[128:131], v[186:189], v[52:55]
	v_mfma_f32_16x16x32_bf16 v[48:51], v[136:139], v[186:189], v[48:51]
	v_mfma_f32_16x16x32_bf16 v[36:39], v[128:131], v[194:197], v[36:39]
	v_mfma_f32_16x16x32_bf16 v[32:35], v[136:139], v[194:197], v[32:35]
	v_mfma_f32_16x16x32_bf16 v[20:23], v[128:131], v[202:205], v[20:23]
	v_mfma_f32_16x16x32_bf16 v[16:19], v[136:139], v[202:205], v[16:19]
	v_mfma_f32_16x16x32_bf16 v[60:63], v[132:135], v[182:185], v[60:63]
	v_mfma_f32_16x16x32_bf16 v[56:59], v[140:143], v[182:185], v[56:59]
	v_mfma_f32_16x16x32_bf16 v[52:55], v[132:135], v[190:193], v[52:55]
	v_mfma_f32_16x16x32_bf16 v[48:51], v[140:143], v[190:193], v[48:51]
	v_mfma_f32_16x16x32_bf16 v[36:39], v[132:135], v[198:201], v[36:39]
	v_mfma_f32_16x16x32_bf16 v[32:35], v[140:143], v[198:201], v[32:35]
	v_mfma_f32_16x16x32_bf16 v[20:23], v[132:135], v[208:211], v[20:23]
	v_mfma_f32_16x16x32_bf16 v[16:19], v[140:143], v[208:211], v[16:19]
	v_mfma_f32_16x16x32_bf16 v[44:47], v[144:147], v[172:175], v[44:47]
	v_mfma_f32_16x16x32_bf16 v[40:43], v[164:167], v[172:175], v[40:43]
	v_mfma_f32_16x16x32_bf16 v[28:31], v[144:147], v[186:189], v[28:31]
	v_mfma_f32_16x16x32_bf16 v[24:27], v[164:167], v[186:189], v[24:27]
	v_mfma_f32_16x16x32_bf16 v[12:15], v[144:147], v[194:197], v[12:15]
	v_mfma_f32_16x16x32_bf16 v[8:11], v[164:167], v[194:197], v[8:11]
	v_mfma_f32_16x16x32_bf16 v[4:7], v[144:147], v[202:205], v[4:7]
	v_mfma_f32_16x16x32_bf16 v[0:3], v[164:167], v[202:205], v[0:3]
	v_mfma_f32_16x16x32_bf16 v[44:47], v[160:163], v[182:185], v[44:47]
	v_mfma_f32_16x16x32_bf16 v[40:43], v[168:171], v[182:185], v[40:43]
	v_mfma_f32_16x16x32_bf16 v[28:31], v[160:163], v[190:193], v[28:31]
	v_mfma_f32_16x16x32_bf16 v[24:27], v[168:171], v[190:193], v[24:27]
	v_mfma_f32_16x16x32_bf16 v[12:15], v[160:163], v[198:201], v[12:15]
	v_mfma_f32_16x16x32_bf16 v[8:11], v[168:171], v[198:201], v[8:11]
	v_mfma_f32_16x16x32_bf16 v[4:7], v[160:163], v[208:211], v[4:7]
	v_mfma_f32_16x16x32_bf16 v[0:3], v[168:171], v[208:211], v[0:3]
	s_barrier
	s_add_u32 s36, s36, 0x100
	s_addc_u32 s37, s37, 0
	s_cmp_ge_u32 s38, s34
	s_mov_b64 s[18:19], s[4:5]
	s_mov_b32 s6, s38
	s_cbranch_scc0 .LBB0_1068
	v_readlane_b32 s4, v249, 25
	v_readlane_b32 s5, v249, 26
	s_and_b64 vcc, exec, s[4:5]
	s_cbranch_vccz .LBB0_1071
	s_barrier
